# baseline (speedup 1.0000x reference)
; #define w_ada KARG(4)
; __global__ void __launch_bounds__(NTHR, 2) mk_fwd(Args a) {
;     ...
;             for (int it = bid; it < 768; it += G) {
;                 const int l = it / 192, cc = it % 192; const float* W = w_ada + (size_t)l * 1024 * 6144 + cc * 32;
;                 const int col = tid & 31, ks = tid >> 5; float acc[5] = {0.f, 0.f, 0.f, 0.f, 0.f};
; #pragma unroll 16
;                 for (int k = ks * 64; k < ks * 64 + 64; ++k) { const float w = W[(size_t)k * 6144 + col];
; #pragma unroll
;                     for (int j = 0; j < 5; ++j) acc[j] += ssilu[j * 1024 + k] * w; }
.LBB0_16:
	v_lshl_add_u64 v[68:69], v[62:63], 0, s[12:13]
	v_add_co_u32_e64 v102, s[4:5], s0, v68
	ds_read_b128 v[18:21], v70
	ds_read_b128 v[14:17], v70 offset:16
	ds_read_b128 v[10:13], v70 offset:32
	ds_read_b128 v[6:9], v70 offset:48
	ds_read_b128 v[2:5], v70 offset:4096
	ds_read_b128 v[22:25], v70 offset:4112
	ds_read_b128 v[38:41], v70 offset:8192
	ds_read_b128 v[34:37], v70 offset:8208
	ds_read_b128 v[30:33], v70 offset:12288
	ds_read_b128 v[26:29], v70 offset:12304
	ds_read_b128 v[46:49], v70 offset:16384
	ds_read_b128 v[42:45], v70 offset:16400
	ds_read_b128 v[50:53], v70 offset:4128
	ds_read_b128 v[72:75], v70 offset:4144
	ds_read_b128 v[76:79], v70 offset:8224
	ds_read_b128 v[80:83], v70 offset:8240
	ds_read_b128 v[84:87], v70 offset:12320
	ds_read_b128 v[88:91], v70 offset:12336
	ds_read_b128 v[92:95], v70 offset:16416
	ds_read_b128 v[96:99], v70 offset:16432
	v_addc_co_u32_e64 v103, s[4:5], 0, v69, s[4:5]
	v_add_co_u32_e64 v104, s[4:5], s1, v68
	global_load_dword v100, v[68:69], off
	s_nop 0
	v_addc_co_u32_e64 v105, s[4:5], 0, v69, s[4:5]
	v_add_co_u32_e64 v106, s[4:5], s20, v68
	s_add_u32 s12, s12, 0x60000
	s_nop 0
	v_addc_co_u32_e64 v107, s[4:5], 0, v69, s[4:5]
	v_add_co_u32_e64 v108, s[4:5], s21, v68
	s_addc_u32 s13, s13, 0
	s_nop 0
	v_addc_co_u32_e64 v109, s[4:5], 0, v69, s[4:5]
	v_add_co_u32_e64 v110, s[4:5], s22, v68
	v_add_u32_e32 v70, 64, v70
	s_nop 0
	v_addc_co_u32_e64 v111, s[4:5], 0, v69, s[4:5]
	v_add_co_u32_e64 v112, s[4:5], s23, v68
	s_cmp_eq_u32 s12, 0x180000
	s_nop 0
	v_addc_co_u32_e64 v113, s[4:5], 0, v69, s[4:5]
	v_add_co_u32_e64 v114, s[4:5], s24, v68
	s_waitcnt lgkmcnt(0)
	s_nop 0
	v_addc_co_u32_e64 v115, s[4:5], 0, v69, s[4:5]
	v_add_co_u32_e64 v116, s[4:5], s25, v68
	s_nop 1
	v_addc_co_u32_e64 v117, s[4:5], 0, v69, s[4:5]
	v_add_co_u32_e64 v118, s[4:5], s26, v68
	s_nop 1
	v_addc_co_u32_e64 v119, s[4:5], 0, v69, s[4:5]
	v_add_co_u32_e64 v120, s[4:5], s27, v68
	s_nop 1
	v_addc_co_u32_e64 v121, s[4:5], 0, v69, s[4:5]
	v_add_co_u32_e64 v122, s[4:5], s28, v68
	s_nop 1
	v_addc_co_u32_e64 v123, s[4:5], 0, v69, s[4:5]
	v_add_co_u32_e64 v124, s[4:5], s29, v68
	s_nop 1
	v_addc_co_u32_e64 v125, s[4:5], 0, v69, s[4:5]
	v_add_co_u32_e64 v126, s[4:5], s30, v68
	s_nop 1
	v_addc_co_u32_e64 v127, s[4:5], 0, v69, s[4:5]
	v_add_co_u32_e64 v128, s[4:5], s31, v68
	s_nop 1
	v_addc_co_u32_e64 v129, s[4:5], 0, v69, s[4:5]
	v_add_co_u32_e64 v68, s[4:5], s33, v68
	s_nop 1
	v_addc_co_u32_e64 v69, s[4:5], 0, v69, s[4:5]
	global_load_dword v102, v[102:103], off
	s_nop 0
	global_load_dword v104, v[104:105], off
	s_nop 0
	global_load_dword v106, v[106:107], off
	s_nop 0
	global_load_dword v108, v[108:109], off
	s_nop 0
	global_load_dword v130, v[110:111], off
	global_load_dword v132, v[112:113], off
	s_nop 0
	global_load_dword v110, v[114:115], off
	global_load_dword v112, v[116:117], off
	global_load_dword v134, v[118:119], off
	global_load_dword v136, v[120:121], off
	s_nop 0
	global_load_dword v114, v[122:123], off
	global_load_dword v116, v[124:125], off
	global_load_dword v118, v[126:127], off
	global_load_dword v120, v[128:129], off
	global_load_dword v138, v[68:69], off
	v_mov_b32_e32 v68, v18
	v_mov_b32_e32 v69, v2
	v_mov_b32_e32 v2, v19
	v_mov_b32_e32 v18, v20
	v_mov_b32_e32 v19, v4
	v_mov_b32_e32 v4, v21
	v_mov_b32_e32 v20, v38
	v_mov_b32_e32 v21, v30
	v_mov_b32_e32 v30, v39
	v_mov_b32_e32 v38, v40
	v_mov_b32_e32 v39, v32
	v_mov_b32_e32 v32, v41
	v_mov_b32_e32 v40, v14
	v_mov_b32_e32 v41, v22
	v_mov_b32_e32 v22, v15
	v_mov_b32_e32 v14, v16
	v_mov_b32_e32 v15, v24
	v_mov_b32_e32 v24, v17
	v_mov_b32_e32 v16, v34
	v_mov_b32_e32 v17, v26
	v_mov_b32_e32 v26, v35
	v_mov_b32_e32 v34, v36
	v_mov_b32_e32 v35, v28
	v_mov_b32_e32 v28, v37
	v_mov_b32_e32 v36, v10
	v_mov_b32_e32 v37, v50
	v_mov_b32_e32 v50, v11
	v_mov_b32_e32 v10, v12
	v_mov_b32_e32 v11, v52
	v_mov_b32_e32 v52, v13
	v_mov_b32_e32 v12, v76
	v_mov_b32_e32 v13, v84
	v_mov_b32_e32 v84, v77
	v_mov_b32_e32 v76, v78
	v_mov_b32_e32 v77, v86
	v_mov_b32_e32 v86, v79
	v_mov_b32_e32 v78, v6
	v_mov_b32_e32 v79, v72
	v_mov_b32_e32 v72, v7
	v_mov_b32_e32 v6, v8
	v_mov_b32_e32 v7, v74
	v_mov_b32_e32 v74, v9
	v_mov_b32_e32 v8, v80
	v_mov_b32_e32 v9, v88
	v_mov_b32_e32 v88, v81
	v_mov_b32_e32 v80, v82
	v_mov_b32_e32 v81, v90
	v_mov_b32_e32 v90, v83
	s_waitcnt vmcnt(0) lgkmcnt(0)
; #define b_ada KARG(5)
; __global__ void __launch_bounds__(NTHR, 2) mk_fwd(Args a) {
;     ...
; #pragma unroll 16
;                 for (int k = ks * 64; k < ks * 64 + 64; ++k) { const float w = W[(size_t)k * 6144 + col];
; #pragma unroll
;                     for (int j = 0; j < 5; ++j) acc[j] += ssilu[j * 1024 + k] * w; }
; #pragma unroll
;                 for (int j = 0; j < 5; ++j) red[(ks * 5 + j) * 32 + col] = acc[j];
;                 __syncthreads();
;                 if (tid < 160) { const int j = tid >> 5, cl = tid & 31; float s = 0.f;
;                     for (int k2 = 0; k2 < 16; ++k2) s += red[(k2 * 5 + j) * 32 + cl];
;                     mods[(l * 5 + j) * 6144 + cc * 32 + cl] = s + b_ada[l * 6144 + cc * 32 + cl]; }
	v_fmac_f32_e32 v71, v100, v46
	v_pk_fma_f32 v[64:65], v[100:101], v[68:69], v[64:65] op_sel_hi:[0,1,1]
	v_pk_fma_f32 v[20:21], v[100:101], v[20:21], v[66:67] op_sel_hi:[0,1,1]
	v_pk_fma_f32 v[2:3], v[102:103], v[2:3], v[64:65] op_sel_hi:[0,1,1]
	v_pk_fma_f32 v[20:21], v[102:103], v[30:31], v[20:21] op_sel_hi:[0,1,1]
	v_fmac_f32_e32 v71, v102, v47
	v_pk_fma_f32 v[2:3], v[104:105], v[18:19], v[2:3] op_sel_hi:[0,1,1]
	v_pk_fma_f32 v[18:19], v[104:105], v[38:39], v[20:21] op_sel_hi:[0,1,1]
	v_fmac_f32_e32 v71, v104, v48
	v_pk_fma_f32 v[2:3], v[106:107], v[4:5], v[2:3] op_sel_hi:[0,1,1]
	v_pk_fma_f32 v[4:5], v[106:107], v[32:33], v[18:19] op_sel_hi:[0,1,1]
	v_fmac_f32_e32 v71, v106, v49
	v_pk_fma_f32 v[2:3], v[108:109], v[40:41], v[2:3] op_sel_hi:[0,1,1]
	v_pk_fma_f32 v[4:5], v[108:109], v[16:17], v[4:5] op_sel_hi:[0,1,1]
	v_fmac_f32_e32 v71, v108, v42
	v_pk_fma_f32 v[2:3], v[130:131], v[22:23], v[2:3] op_sel_hi:[0,1,1]
	v_pk_fma_f32 v[4:5], v[130:131], v[26:27], v[4:5] op_sel_hi:[0,1,1]
	v_fmac_f32_e32 v71, v130, v43
	v_pk_fma_f32 v[2:3], v[132:133], v[14:15], v[2:3] op_sel_hi:[0,1,1]
	v_pk_fma_f32 v[4:5], v[132:133], v[34:35], v[4:5] op_sel_hi:[0,1,1]
	v_fmac_f32_e32 v71, v132, v44
	v_pk_fma_f32 v[2:3], v[110:111], v[24:25], v[2:3] op_sel_hi:[0,1,1]
	v_pk_fma_f32 v[4:5], v[110:111], v[28:29], v[4:5] op_sel_hi:[0,1,1]
	v_fmac_f32_e32 v71, v110, v45
	v_pk_fma_f32 v[2:3], v[112:113], v[36:37], v[2:3] op_sel_hi:[0,1,1]
	v_pk_fma_f32 v[4:5], v[112:113], v[12:13], v[4:5] op_sel_hi:[0,1,1]
	v_fmac_f32_e32 v71, v112, v92
	v_pk_fma_f32 v[2:3], v[134:135], v[50:51], v[2:3] op_sel_hi:[0,1,1]
	v_pk_fma_f32 v[4:5], v[134:135], v[84:85], v[4:5] op_sel_hi:[0,1,1]
	v_fmac_f32_e32 v71, v134, v93
	v_pk_fma_f32 v[2:3], v[136:137], v[10:11], v[2:3] op_sel_hi:[0,1,1]
	v_pk_fma_f32 v[4:5], v[136:137], v[76:77], v[4:5] op_sel_hi:[0,1,1]
	v_fmac_f32_e32 v71, v136, v94
	v_pk_fma_f32 v[2:3], v[114:115], v[52:53], v[2:3] op_sel_hi:[0,1,1]
	v_pk_fma_f32 v[4:5], v[114:115], v[86:87], v[4:5] op_sel_hi:[0,1,1]
	v_fmac_f32_e32 v71, v114, v95
	v_pk_fma_f32 v[2:3], v[116:117], v[78:79], v[2:3] op_sel_hi:[0,1,1]
	v_pk_fma_f32 v[4:5], v[116:117], v[8:9], v[4:5] op_sel_hi:[0,1,1]
	v_fmac_f32_e32 v71, v116, v96
	v_pk_fma_f32 v[2:3], v[118:119], v[72:73], v[2:3] op_sel_hi:[0,1,1]
	v_pk_fma_f32 v[4:5], v[118:119], v[88:89], v[4:5] op_sel_hi:[0,1,1]
	v_fmac_f32_e32 v71, v118, v97
	v_pk_fma_f32 v[2:3], v[120:121], v[6:7], v[2:3] op_sel_hi:[0,1,1]
	v_pk_fma_f32 v[4:5], v[120:121], v[80:81], v[4:5] op_sel_hi:[0,1,1]
	v_fmac_f32_e32 v71, v120, v98
	v_pk_fma_f32 v[64:65], v[138:139], v[74:75], v[2:3] op_sel_hi:[0,1,1]
	v_pk_fma_f32 v[66:67], v[138:139], v[90:91], v[4:5] op_sel_hi:[0,1,1]
	v_fmac_f32_e32 v71, v138, v99
	s_cbranch_scc0 .LBB0_16
	v_add_u32_e32 v2, 0x5000, v57
	ds_write2_b32 v2, v64, v65 offset1:32
	ds_write2_b32 v2, v66, v67 offset0:64 offset1:96
	ds_write_b32 v57, v71 offset:20992
	s_waitcnt lgkmcnt(0)
	s_barrier
	s_and_saveexec_b64 s[4:5], vcc
	s_cbranch_execz .LBB0_14
	s_load_dwordx2 s[12:13], s[16:17], 0x28
	s_mul_i32 s11, s36, 0x1800
	s_add_i32 s11, s11, s10
	v_or_b32_e32 v2, s11, v54
	v_ashrrev_i32_e32 v3, 31, v2
	s_waitcnt lgkmcnt(0)
	v_lshl_add_u64 v[2:3], v[2:3], 2, s[12:13]
	global_load_dword v20, v[2:3], off
	v_add_u32_e32 v4, 0x5000, v59
	v_add_u32_e32 v6, 0x5400, v59
	v_add_u32_e32 v8, 0x5a00, v59
	v_add_u32_e32 v10, 0x5e00, v59
	v_add_u32_e32 v12, 0x6400, v59
	v_add_u32_e32 v14, 0x6800, v59
	v_add_u32_e32 v16, 0x6e00, v59
	v_add_u32_e32 v18, 0x7200, v59
	ds_read2_b32 v[4:5], v4 offset1:160
	ds_read2_b32 v[6:7], v6 offset0:64 offset1:224
	ds_read2_b32 v[8:9], v8 offset1:160
	ds_read2_b32 v[10:11], v10 offset0:64 offset1:224
	ds_read2_b32 v[12:13], v12 offset1:160
	ds_read2_b32 v[14:15], v14 offset0:64 offset1:224
	ds_read2_b32 v[16:17], v16 offset1:160
	ds_read2_b32 v[18:19], v18 offset0:64 offset1:224
	s_waitcnt lgkmcnt(0)
	v_add_f32_e32 v4, 0, v4
	v_add_f32_e32 v4, v4, v5
	v_add_f32_e32 v4, v4, v6
	v_add_f32_e32 v4, v4, v7
	v_add_f32_e32 v4, v4, v8
	v_add_f32_e32 v4, v4, v9
	v_add_f32_e32 v4, v4, v10
	v_add_f32_e32 v4, v4, v11
	v_add_f32_e32 v4, v4, v12
	v_add_f32_e32 v4, v4, v13
	v_add_f32_e32 v4, v4, v14
	v_mad_u64_u32 v[2:3], s[12:13], s36, 5, v[58:59]
	v_add_f32_e32 v4, v4, v15
	v_mul_lo_u32 v2, v2, s34
	v_add_f32_e32 v4, v4, v16
	v_add_u32_e32 v2, s10, v2
	v_add_f32_e32 v4, v4, v17
	v_or_b32_e32 v2, v2, v54
	v_add_f32_e32 v4, v4, v18
	v_ashrrev_i32_e32 v3, 31, v2
	v_add_f32_e32 v4, v4, v19
	v_lshl_add_u64 v[2:3], v[2:3], 2, s[6:7]
	s_waitcnt vmcnt(0)
	v_add_f32_e32 v4, v4, v20
	global_store_dword v[2:3], v4, off
	s_branch .LBB0_14

; #define LAS __attribute__((address_space(3)))
; __device__ __forceinline__ float lane_xor(float v, int lane, int o) { return __int_as_float(__builtin_amdgcn_ds_bpermute((lane ^ o) << 2, __float_as_int(v))); }
; template <int A0, int A1, int B0, int B1, bool LOC> ...
;     if (LOC) {
; #pragma unroll
;         for (int i = A0; i < A1; ++i) s0[i] += sbp[8 * (i >> 2) + (i & 3)] + mk0[i];
; #pragma unroll
;         for (int i = B0; i < B1; ++i) s1v[i] += sbp[32 + 8 * (i >> 2) + (i & 3)] + mk1[i];
;     }
;     float mx = -1e30f;
; #pragma unroll
;     for (int i = A0; i < A1; ++i) mx = fmaxf(mx, s0[i]);
; #pragma unroll
;     for (int i = B0; i < B1; ++i) mx = fmaxf(mx, s1v[i]);
;     mx = fmaxf(mx, lane_xor(mx, lane, 32));
;     const float mn = fmaxf(m, mx);
;     if (__any(mn > m)) { const float alpha = __builtin_amdgcn_exp2f(m - mn); lsum *= alpha;
; #pragma unroll
;         for (int i = 0; i < 16; ++i) { o0[i] *= alpha; o1[i] *= alpha; } }
; __device__ __forceinline__ void attn_blk(bool ctx_too, const bf16_t* U, bf16_t* Y, const float* nb_l, LAS unsigned char* lds, int lane, int wave, int tid) {
;     ...
;                 for (int kk = 0; kk < 4; ++kk) { const int co = ((2 * kk + hh) ^ ksw) << 4;
;                     const bf16x8 k0 = *(const LAS bf16x8*)(kbuf + kro + co), k1 = *(const LAS bf16x8*)(kbuf + 4096 + kro + co);
;                     s0 = __builtin_amdgcn_mfma_f32_32x32x16_bf16(k0, qf[kk], s0, 0, 0, 0); s1v = __builtin_amdgcn_mfma_f32_32x32x16_bf16(k1, qf[kk], s1v, 0, 0, 0); }
;                 if (st < 4) att_soft_pv<0, 16, 0, 16, false>(s0, s1v, o0, o1, m, lsum, vbuf, vro, vsw, lane, sb, mk0, mk1);
;                 else { const LAS float* sbp = sb + 64 + (h * 15 + (j - r + 7)) * 31 + 4 * hh - c + 15;
;                     if (half == 0) att_soft_pv<0, 16, 0, 4, true>(s0, s1v, o0, o1, m, lsum, vbuf, vro, vsw, lane, sbp, mk0, mk1);
;                     else att_soft_pv<12, 16, 0, 16, true>(s0, s1v, o0, o1, m, lsum, vbuf, vro, vsw, lane, sbp, mk0, mk1); }
.LBB0_485:
	s_andn2_b64 vcc, exec, s[30:31]
	s_cbranch_vccnz .LBB0_501
	v_add_u32_e32 v0, v181, v188
	ds_read_b128 v[36:39], v0 offset:16384
	ds_read_b128 v[40:43], v0 offset:20480
	v_add_u32_e32 v0, v181, v189
	ds_read_b128 v[68:71], v0 offset:16384
	ds_read_b128 v[72:75], v0 offset:20480
	v_add_u32_e32 v0, v181, v190
	s_waitcnt lgkmcnt(0)
	v_mfma_f32_32x32x16_bf16 v[52:67], v[36:39], v[100:103], 0
	s_mov_b64 s[30:31], -1
	s_and_b64 vcc, exec, s[26:27]
	v_mfma_f32_32x32x16_bf16 v[36:51], v[40:43], v[100:103], 0
	v_mfma_f32_32x32x16_bf16 v[52:67], v[68:71], v[104:107], v[52:67]
	v_mfma_f32_32x32x16_bf16 v[36:51], v[72:75], v[104:107], v[36:51]
	ds_read_b128 v[68:71], v0 offset:16384
	ds_read_b128 v[72:75], v0 offset:20480
	v_add_u32_e32 v0, v181, v191
	s_waitcnt lgkmcnt(0)
	v_mfma_f32_32x32x16_bf16 v[52:67], v[68:71], v[108:111], v[52:67]
	v_mfma_f32_32x32x16_bf16 v[36:51], v[72:75], v[108:111], v[36:51]
	ds_read_b128 v[68:71], v0 offset:16384
	ds_read_b128 v[72:75], v0 offset:20480
	s_waitcnt lgkmcnt(0)
	v_mfma_f32_32x32x16_bf16 v[52:67], v[68:71], v[112:115], v[52:67]
	v_mfma_f32_32x32x16_bf16 v[36:51], v[72:75], v[112:115], v[36:51]
	s_cbranch_vccz .LBB0_496
	s_and_b64 vcc, exec, s[4:5]
	s_cbranch_vccz .LBB0_491
	ds_read2_b32 v[0:1], v139 offset0:24 offset1:25
	ds_read2_b32 v[68:69], v139 offset0:26 offset1:27
	ds_read2_b32 v[70:71], v139 offset0:32 offset1:33
	ds_read2_b32 v[72:73], v139 offset0:34 offset1:35
	s_waitcnt lgkmcnt(0)
	v_add_f32_e32 v0, v172, v0
	s_nop 0
	v_add_f32_e32 v218, v64, v0
	v_add_f32_e32 v0, v176, v68
	v_add_f32_e32 v216, v66, v0
	v_add_f32_e32 v0, v178, v69
	v_add_f32_e32 v215, v67, v0
	v_add_f32_e32 v0, v149, v70
	v_add_f32_e32 v214, v36, v0
	v_add_f32_e32 v0, v151, v71
	v_add_f32_e32 v1, v174, v1
	v_add_f32_e32 v213, v37, v0
	v_add_f32_e32 v0, v153, v72
	v_add_f32_e32 v217, v65, v1
	v_add_f32_e32 v206, v38, v0
	ds_read2_b32 v[0:1], v139 offset0:40 offset1:41
	v_add_f32_e32 v3, v155, v73
	ds_read2_b32 v[68:69], v139 offset0:42 offset1:43
	ds_read2_b32 v[70:71], v139 offset0:48 offset1:49
	ds_read2_b32 v[72:73], v139 offset0:50 offset1:51
	v_add_f32_e32 v205, v39, v3
	v_mov_b32_e32 v202, v141
	s_waitcnt lgkmcnt(0)
	v_add_f32_e32 v0, v157, v0
	v_add_f32_e32 v207, v40, v0
	v_add_f32_e32 v0, v159, v1
	v_add_f32_e32 v204, v41, v0
	v_add_f32_e32 v0, v161, v68
	v_add_f32_e32 v203, v42, v0
	v_add_f32_e32 v0, v163, v69
	ds_read2_b32 v[68:69], v139 offset0:56 offset1:57
	v_add_f32_e32 v201, v43, v0
	v_add_f32_e32 v0, v165, v70
	v_add_f32_e32 v200, v44, v0
	v_add_f32_e32 v0, v167, v71
	ds_read2_b32 v[70:71], v139 offset0:58 offset1:59
	s_waitcnt lgkmcnt(0)
	v_add_f32_e32 v68, v173, v68
	v_add_f32_e32 v199, v48, v68
	v_add_f32_e32 v68, v175, v69
	v_add_f32_e32 v198, v49, v68
	v_add_f32_e32 v68, v177, v70
	v_add_f32_e32 v197, v50, v68
	v_add_f32_e32 v68, v179, v71
	v_add_f32_e32 v196, v51, v68
	v_max3_f32 v68, v218, s41, v217
	v_max3_f32 v68, v68, v216, v215
	v_max3_f32 v68, v68, v214, v213
	v_max3_f32 v68, v68, v206, v205
	v_add_f32_e32 v1, v169, v72
	v_max3_f32 v68, v68, v207, v204
	v_add_f32_e32 v0, v45, v0
	v_add_f32_e32 v3, v46, v1
	v_add_f32_e32 v1, v171, v73
	v_max3_f32 v68, v68, v203, v201
	v_add_f32_e32 v1, v47, v1
	v_max3_f32 v68, v68, v200, v0
	v_max3_f32 v68, v68, v3, v1
	v_max3_f32 v68, v68, v199, v198
	v_max3_f32 v68, v68, v197, v196
	ds_bpermute_b32 v69, v182, v68
	s_waitcnt lgkmcnt(0)
	v_max3_f32 v195, v143, v68, v69
	v_cmp_gt_f32_e32 vcc, v195, v143
	s_cbranch_vccz .LBB0_490
	v_sub_f32_e32 v68, v143, v195
	v_exp_f32_e32 v84, v68
	s_nop 0
	v_mul_f32_e32 v202, v141, v84
	v_pk_mul_f32 v[34:35], v[34:35], v[84:85] op_sel_hi:[1,0]
	v_pk_mul_f32 v[32:33], v[32:33], v[84:85] op_sel_hi:[1,0]
	v_pk_mul_f32 v[30:31], v[30:31], v[84:85] op_sel_hi:[1,0]
	v_pk_mul_f32 v[28:29], v[28:29], v[84:85] op_sel_hi:[1,0]
	v_pk_mul_f32 v[26:27], v[26:27], v[84:85] op_sel_hi:[1,0]
	v_pk_mul_f32 v[24:25], v[24:25], v[84:85] op_sel_hi:[1,0]
	v_pk_mul_f32 v[22:23], v[22:23], v[84:85] op_sel_hi:[1,0]
	v_pk_mul_f32 v[20:21], v[20:21], v[84:85] op_sel_hi:[1,0]
	v_pk_mul_f32 v[18:19], v[18:19], v[84:85] op_sel_hi:[1,0]
	v_pk_mul_f32 v[16:17], v[16:17], v[84:85] op_sel_hi:[1,0]
	v_pk_mul_f32 v[14:15], v[14:15], v[84:85] op_sel_hi:[1,0]
	v_pk_mul_f32 v[12:13], v[12:13], v[84:85] op_sel_hi:[1,0]
	v_pk_mul_f32 v[10:11], v[10:11], v[84:85] op_sel_hi:[1,0]
	v_pk_mul_f32 v[8:9], v[8:9], v[84:85] op_sel_hi:[1,0]
	v_pk_mul_f32 v[6:7], v[6:7], v[84:85] op_sel_hi:[1,0]
	v_pk_mul_f32 v[4:5], v[4:5], v[84:85] op_sel_hi:[1,0]
; __device__ __forceinline__ unsigned pk2(float lo, float hi) { const f32x2_t v = {lo, hi}; return __builtin_bit_cast(unsigned, __builtin_convertvector(v, bf16x2_t)); }
; template <int A0, int A1, int B0, int B1, bool LOC> ...
;     ...
;     m = mn;
;     float ps = 0.f;
; #pragma unroll
;     for (int i = 0; i < 16; ++i) { if (i >= A0 && i < A1) { s0[i] = __builtin_amdgcn_exp2f(s0[i] - mn); ps += s0[i]; } else s0[i] = 0.f; }
; #pragma unroll
;     for (int i = 0; i < 16; ++i) { if (i >= B0 && i < B1) { s1v[i] = __builtin_amdgcn_exp2f(s1v[i] - mn); ps += s1v[i]; } else s1v[i] = 0.f; }
;     lsum += ps;
; #pragma unroll
;     for (int kk = 0; kk < 4; ++kk) {
;         const int o = 8 * (kk & 1); const bool live = (kk < 2) ? (o < A1 && o + 8 > A0) : (o < B1 && o + 8 > B0);
;         if (!live) continue;
;         u32x4 pw;
;         if (kk < 2) { pw.x = pk2(s0[o], s0[o + 1]); pw.y = pk2(s0[o + 2], s0[o + 3]); pw.z = pk2(s0[o + 4], s0[o + 5]); pw.w = pk2(s0[o + 6], s0[o + 7]); }
;         else { pw.x = pk2(s1v[o], s1v[o + 1]); pw.y = pk2(s1v[o + 2], s1v[o + 3]); pw.z = pk2(s1v[o + 4], s1v[o + 5]); pw.w = pk2(s1v[o + 6], s1v[o + 7]); }
;         const bf16x8 pf = __builtin_bit_cast(bf16x8, pw);
;         const bf16x8 v0 = tr2(vbuf + kk * 2048 + vro + ((0 ^ vsw) * 64), 1024), v1 = tr2(vbuf + kk * 2048 + vro + ((1 ^ vsw) * 64), 1024);
;         o0 = __builtin_amdgcn_mfma_f32_32x32x16_bf16(v0, pf, o0, 0, 0, 0);
;         o1 = __builtin_amdgcn_mfma_f32_32x32x16_bf16(v1, pf, o1, 0, 0, 0);
;     }
.LBB0_490:
	v_sub_f32_e32 v218, v218, v195
	v_exp_f32_e32 v218, v218
	v_sub_f32_e32 v217, v217, v195
	v_exp_f32_e32 v217, v217
	v_sub_f32_e32 v216, v216, v195
	v_exp_f32_e32 v216, v216
	v_sub_f32_e32 v215, v215, v195
	v_exp_f32_e32 v215, v215
	v_sub_f32_e32 v214, v214, v195
	v_add_f32_e32 v219, 0, v218
	v_exp_f32_e32 v220, v214
	v_add_f32_e32 v219, v217, v219
	v_sub_f32_e32 v213, v213, v195
	v_add_f32_e32 v219, v216, v219
	v_exp_f32_e32 v213, v213
	v_sub_f32_e32 v206, v206, v195
	v_add_f32_e32 v219, v215, v219
	v_exp_f32_e32 v206, v206
	v_sub_f32_e32 v205, v205, v195
	v_add_f32_e32 v214, v220, v219
	v_exp_f32_e32 v219, v205
	v_sub_f32_e32 v207, v207, v195
	v_exp_f32_e32 v207, v207
	v_sub_f32_e32 v204, v204, v195
	v_add_f32_e32 v214, v213, v214
	v_exp_f32_e32 v221, v204
	v_sub_f32_e32 v203, v203, v195
	v_add_f32_e32 v214, v206, v214
	v_exp_f32_e32 v222, v203
	v_sub_f32_e32 v201, v201, v195
	v_add_f32_e32 v205, v219, v214
	v_exp_f32_e32 v223, v201
	v_sub_f32_e32 v200, v200, v195
	v_add_f32_e32 v205, v207, v205
	v_exp_f32_e32 v224, v200
	v_sub_f32_e32 v0, v0, v195
	v_add_f32_e32 v204, v221, v205
	v_exp_f32_e32 v0, v0
	v_sub_f32_e32 v3, v3, v195
	v_add_f32_e32 v203, v222, v204
	v_exp_f32_e32 v3, v3
	v_sub_f32_e32 v1, v1, v195
	v_add_f32_e32 v201, v223, v203
	v_exp_f32_e32 v1, v1
	v_sub_f32_e32 v199, v199, v195
	v_add_f32_e32 v200, v224, v201
	v_exp_f32_e32 v225, v199
	v_sub_f32_e32 v198, v198, v195
	v_add_f32_e32 v200, v0, v200
	v_exp_f32_e32 v226, v198
	v_sub_f32_e32 v197, v197, v195
	v_add_f32_e32 v200, v3, v200
	v_exp_f32_e32 v197, v197
	v_sub_f32_e32 v196, v196, v195
	v_add_f32_e32 v200, v1, v200
	v_exp_f32_e32 v227, v196
	v_add_f32_e32 v199, v225, v200
	v_add_f32_e32 v198, v226, v199
	v_add_f32_e32 v198, v197, v198
	v_add_f32_e32 v196, v227, v198
	v_cvt_pk_bf16_f32 v200, v218, v217
	v_add_u32_e32 v218, v183, v184
	v_add_u32_e32 v228, v183, v185
	v_add_f32_e32 v196, v196, v202
	v_cvt_pk_bf16_f32 v201, v216, v215
	ds_read_b64_tr_b16 v[202:203], v218 offset:34816
	ds_read_b64_tr_b16 v[204:205], v218 offset:35840
	ds_read_b64_tr_b16 v[214:215], v228 offset:34816
	ds_read_b64_tr_b16 v[216:217], v228 offset:35840
	v_mov_b32_e32 v198, v2
	v_mov_b32_e32 v199, v2
	s_waitcnt lgkmcnt(0)
	s_nop 0
	v_mfma_f32_32x32x16_bf16 v[20:35], v[202:205], v[198:201], v[20:35]
	v_mfma_f32_32x32x16_bf16 v[4:19], v[214:217], v[198:201], v[4:19]
	ds_read_b64_tr_b16 v[202:203], v218 offset:36864
	ds_read_b64_tr_b16 v[204:205], v218 offset:37888
	ds_read_b64_tr_b16 v[214:215], v228 offset:36864
	ds_read_b64_tr_b16 v[216:217], v228 offset:37888
	v_cvt_pk_bf16_f32 v198, v220, v213
	v_cvt_pk_bf16_f32 v199, v206, v219
	v_cvt_pk_bf16_f32 v200, v207, v221
	v_cvt_pk_bf16_f32 v201, v222, v223
	s_waitcnt lgkmcnt(0)
	s_nop 0
	v_mfma_f32_32x32x16_bf16 v[20:35], v[202:205], v[198:201], v[20:35]
	v_mfma_f32_32x32x16_bf16 v[4:19], v[214:217], v[198:201], v[4:19]
	ds_read_b64_tr_b16 v[202:203], v218 offset:38912
	ds_read_b64_tr_b16 v[204:205], v218 offset:39936
	ds_read_b64_tr_b16 v[214:215], v228 offset:38912
	ds_read_b64_tr_b16 v[216:217], v228 offset:39936
	v_cvt_pk_bf16_f32 v198, v224, v0
	v_cvt_pk_bf16_f32 v199, v3, v1
	v_cvt_pk_bf16_f32 v200, v225, v226
	v_cvt_pk_bf16_f32 v201, v197, v227
	s_waitcnt lgkmcnt(0)
	s_nop 0
	v_mfma_f32_32x32x16_bf16 v[20:35], v[202:205], v[198:201], v[20:35]
	v_mfma_f32_32x32x16_bf16 v[4:19], v[214:217], v[198:201], v[4:19]
	s_branch .LBB0_495
; __device__ __forceinline__ unsigned pk2(float lo, float hi) { const f32x2_t v = {lo, hi}; return __builtin_bit_cast(unsigned, __builtin_convertvector(v, bf16x2_t)); }
; __device__ __forceinline__ float lane_xor(float v, int lane, int o) { return __int_as_float(__builtin_amdgcn_ds_bpermute((lane ^ o) << 2, __float_as_int(v))); }
; template <int A0, int A1, int B0, int B1, bool LOC> ...
;     if (LOC) {
; #pragma unroll
;         for (int i = A0; i < A1; ++i) s0[i] += sbp[8 * (i >> 2) + (i & 3)] + mk0[i];
; #pragma unroll
;         for (int i = B0; i < B1; ++i) s1v[i] += sbp[32 + 8 * (i >> 2) + (i & 3)] + mk1[i];
;     }
;     float mx = -1e30f;
; #pragma unroll
;     for (int i = A0; i < A1; ++i) mx = fmaxf(mx, s0[i]);
; #pragma unroll
;     for (int i = B0; i < B1; ++i) mx = fmaxf(mx, s1v[i]);
;     mx = fmaxf(mx, lane_xor(mx, lane, 32));
;     const float mn = fmaxf(m, mx);
;     if (__any(mn > m)) { const float alpha = __builtin_amdgcn_exp2f(m - mn); lsum *= alpha;
; #pragma unroll
;         for (int i = 0; i < 16; ++i) { o0[i] *= alpha; o1[i] *= alpha; } }
;     m = mn;
;     float ps = 0.f;
; #pragma unroll
;     for (int i = 0; i < 16; ++i) { if (i >= A0 && i < A1) { s0[i] = __builtin_amdgcn_exp2f(s0[i] - mn); ps += s0[i]; } else s0[i] = 0.f; }
; #pragma unroll
;     for (int i = 0; i < 16; ++i) { if (i >= B0 && i < B1) { s1v[i] = __builtin_amdgcn_exp2f(s1v[i] - mn); ps += s1v[i]; } else s1v[i] = 0.f; }
;     lsum += ps;
; #pragma unroll
;     for (int kk = 0; kk < 4; ++kk) {
;         const int o = 8 * (kk & 1); const bool live = (kk < 2) ? (o < A1 && o + 8 > A0) : (o < B1 && o + 8 > B0);
;         if (!live) continue;
;         u32x4 pw;
;         if (kk < 2) { pw.x = pk2(s0[o], s0[o + 1]); pw.y = pk2(s0[o + 2], s0[o + 3]); pw.z = pk2(s0[o + 4], s0[o + 5]); pw.w = pk2(s0[o + 6], s0[o + 7]); }
;         else { pw.x = pk2(s1v[o], s1v[o + 1]); pw.y = pk2(s1v[o + 2], s1v[o + 3]); pw.z = pk2(s1v[o + 4], s1v[o + 5]); pw.w = pk2(s1v[o + 6], s1v[o + 7]); }
;         const bf16x8 pf = __builtin_bit_cast(bf16x8, pw);
;         const bf16x8 v0 = tr2(vbuf + kk * 2048 + vro + ((0 ^ vsw) * 64), 1024), v1 = tr2(vbuf + kk * 2048 + vro + ((1 ^ vsw) * 64), 1024);
;         o0 = __builtin_amdgcn_mfma_f32_32x32x16_bf16(v0, pf, o0, 0, 0, 0);
;         o1 = __builtin_amdgcn_mfma_f32_32x32x16_bf16(v1, pf, o1, 0, 0, 0);
;     }
.LBB0_491:
	s_and_b64 vcc, exec, s[30:31]
	s_cbranch_vccz .LBB0_495
	ds_read2_b32 v[0:1], v139 offset1:1
	ds_read2_b32 v[68:69], v139 offset0:2 offset1:3
	ds_read2_b32 v[70:71], v139 offset0:8 offset1:9
	ds_read2_b32 v[72:73], v139 offset0:10 offset1:11
	s_waitcnt lgkmcnt(0)
	v_add_f32_e32 v0, v148, v0
	v_add_f32_e32 v1, v150, v1
	v_add_f32_e32 v199, v52, v0
	v_add_f32_e32 v0, v53, v1
	v_add_f32_e32 v1, v152, v68
	v_add_f32_e32 v68, v156, v70
	v_add_f32_e32 v196, v56, v68
	v_add_f32_e32 v68, v158, v71
	v_add_f32_e32 v197, v57, v68
	v_add_f32_e32 v68, v160, v72
	v_add_f32_e32 v3, v154, v69
	v_add_f32_e32 v198, v58, v68
	ds_read2_b32 v[68:69], v139 offset0:16 offset1:17
	v_add_f32_e32 v70, v162, v73
	v_add_f32_e32 v200, v59, v70
	ds_read2_b32 v[70:71], v139 offset0:18 offset1:19
	ds_read2_b32 v[72:73], v139 offset0:24 offset1:25
	ds_read2_b32 v[74:75], v139 offset0:26 offset1:27
	v_add_f32_e32 v1, v54, v1
	s_waitcnt lgkmcnt(0)
	v_add_f32_e32 v68, v164, v68
	v_add_f32_e32 v205, v60, v68
	v_add_f32_e32 v68, v166, v69
	v_add_f32_e32 v206, v61, v68
	v_add_f32_e32 v68, v168, v70
	v_add_f32_e32 v207, v62, v68
	v_add_f32_e32 v68, v170, v71
	v_add_f32_e32 v213, v63, v68
	v_add_f32_e32 v68, v172, v72
	v_add_f32_e32 v214, v64, v68
	v_add_f32_e32 v68, v174, v73
	v_add_f32_e32 v215, v65, v68
	v_add_f32_e32 v70, v176, v74
	ds_read2_b32 v[68:69], v139 offset0:32 offset1:33
	v_add_f32_e32 v216, v66, v70
	v_add_f32_e32 v70, v178, v75
	v_add_f32_e32 v217, v67, v70
	ds_read2_b32 v[70:71], v139 offset0:34 offset1:35
	s_waitcnt lgkmcnt(0)
	v_add_f32_e32 v68, v149, v68
	v_add_f32_e32 v204, v36, v68
	v_add_f32_e32 v68, v151, v69
	v_add_f32_e32 v203, v37, v68
	v_add_f32_e32 v68, v153, v70
	v_add_f32_e32 v202, v38, v68
	v_add_f32_e32 v68, v155, v71
	v_add_f32_e32 v3, v55, v3
	v_add_f32_e32 v201, v39, v68
	v_max3_f32 v68, v199, s41, v0
	v_max3_f32 v68, v68, v1, v3
	v_max3_f32 v68, v68, v196, v197
	v_max3_f32 v68, v68, v198, v200
	v_max3_f32 v68, v68, v205, v206
	v_max3_f32 v68, v68, v207, v213
	v_max3_f32 v68, v68, v214, v215
	v_max3_f32 v68, v68, v216, v217
	v_max3_f32 v68, v68, v204, v203
	v_max3_f32 v68, v68, v202, v201
	ds_bpermute_b32 v69, v182, v68
	v_mov_b32_e32 v218, v141
	s_waitcnt lgkmcnt(0)
	v_max3_f32 v195, v143, v68, v69
	v_cmp_gt_f32_e32 vcc, v195, v143
	s_cbranch_vccz .LBB0_494
	v_sub_f32_e32 v68, v143, v195
	v_exp_f32_e32 v84, v68
	s_nop 0
	v_mul_f32_e32 v218, v141, v84
	v_pk_mul_f32 v[34:35], v[34:35], v[84:85] op_sel_hi:[1,0]
	v_pk_mul_f32 v[32:33], v[32:33], v[84:85] op_sel_hi:[1,0]
	v_pk_mul_f32 v[30:31], v[30:31], v[84:85] op_sel_hi:[1,0]
	v_pk_mul_f32 v[28:29], v[28:29], v[84:85] op_sel_hi:[1,0]
	v_pk_mul_f32 v[26:27], v[26:27], v[84:85] op_sel_hi:[1,0]
	v_pk_mul_f32 v[24:25], v[24:25], v[84:85] op_sel_hi:[1,0]
	v_pk_mul_f32 v[22:23], v[22:23], v[84:85] op_sel_hi:[1,0]
	v_pk_mul_f32 v[20:21], v[20:21], v[84:85] op_sel_hi:[1,0]
	v_pk_mul_f32 v[18:19], v[18:19], v[84:85] op_sel_hi:[1,0]
	v_pk_mul_f32 v[16:17], v[16:17], v[84:85] op_sel_hi:[1,0]
	v_pk_mul_f32 v[14:15], v[14:15], v[84:85] op_sel_hi:[1,0]
	v_pk_mul_f32 v[12:13], v[12:13], v[84:85] op_sel_hi:[1,0]
	v_pk_mul_f32 v[10:11], v[10:11], v[84:85] op_sel_hi:[1,0]
	v_pk_mul_f32 v[8:9], v[8:9], v[84:85] op_sel_hi:[1,0]
	v_pk_mul_f32 v[6:7], v[6:7], v[84:85] op_sel_hi:[1,0]
	v_pk_mul_f32 v[4:5], v[4:5], v[84:85] op_sel_hi:[1,0]
.LBB0_494:
	v_sub_f32_e32 v196, v196, v195
	v_exp_f32_e32 v219, v196
	v_sub_f32_e32 v196, v197, v195
	v_exp_f32_e32 v197, v196
	v_sub_f32_e32 v196, v198, v195
	v_exp_f32_e32 v220, v196
	v_sub_f32_e32 v196, v200, v195
	v_exp_f32_e32 v221, v196
	v_sub_f32_e32 v196, v205, v195
	v_exp_f32_e32 v222, v196
	v_sub_f32_e32 v196, v206, v195
	v_exp_f32_e32 v206, v196
	v_sub_f32_e32 v196, v207, v195
	v_sub_f32_e32 v199, v199, v195
	v_exp_f32_e32 v207, v196
	v_sub_f32_e32 v196, v213, v195
	v_exp_f32_e32 v199, v199
	v_sub_f32_e32 v0, v0, v195
	v_exp_f32_e32 v213, v196
	v_sub_f32_e32 v196, v214, v195
	v_exp_f32_e32 v0, v0
	v_sub_f32_e32 v1, v1, v195
	v_exp_f32_e32 v223, v196
	v_sub_f32_e32 v196, v215, v195
	v_exp_f32_e32 v1, v1
	v_sub_f32_e32 v3, v3, v195
	v_exp_f32_e32 v224, v196
	v_sub_f32_e32 v196, v216, v195
	v_exp_f32_e32 v3, v3
	v_exp_f32_e32 v225, v196
	v_sub_f32_e32 v196, v217, v195
	v_exp_f32_e32 v226, v196
	v_add_f32_e32 v196, 0, v199
	v_add_f32_e32 v196, v0, v196
	v_add_f32_e32 v196, v1, v196
	v_add_f32_e32 v196, v3, v196
	v_add_f32_e32 v196, v219, v196
	v_add_f32_e32 v196, v197, v196
	v_add_f32_e32 v196, v220, v196
	v_add_f32_e32 v196, v221, v196
	v_add_f32_e32 v196, v222, v196
	v_add_f32_e32 v196, v206, v196
	v_add_f32_e32 v196, v207, v196
	v_add_f32_e32 v196, v213, v196
	v_sub_f32_e32 v198, v204, v195
	v_add_f32_e32 v196, v223, v196
	v_exp_f32_e32 v227, v198
	v_sub_f32_e32 v198, v203, v195
	v_add_f32_e32 v196, v224, v196
	v_exp_f32_e32 v228, v198
	v_sub_f32_e32 v198, v202, v195
	v_add_f32_e32 v196, v225, v196
	v_exp_f32_e32 v229, v198
	v_sub_f32_e32 v198, v201, v195
	v_add_f32_e32 v196, v226, v196
	v_exp_f32_e32 v230, v198
	v_add_f32_e32 v196, v227, v196
	v_add_f32_e32 v196, v228, v196
	v_add_f32_e32 v196, v229, v196
	v_add_f32_e32 v196, v230, v196
	v_add_f32_e32 v196, v196, v218
	v_cvt_pk_bf16_f32 v200, v219, v197
	v_add_u32_e32 v197, v183, v184
	v_add_u32_e32 v218, v183, v185
	ds_read_b64_tr_b16 v[202:203], v197 offset:32768
	ds_read_b64_tr_b16 v[204:205], v197 offset:33792
	ds_read_b64_tr_b16 v[214:215], v218 offset:32768
	ds_read_b64_tr_b16 v[216:217], v218 offset:33792
	v_cvt_pk_bf16_f32 v198, v199, v0
	v_cvt_pk_bf16_f32 v199, v1, v3
	v_cvt_pk_bf16_f32 v201, v220, v221
	v_cvt_pk_bf16_f32 v0, v227, v228
	v_cvt_pk_bf16_f32 v1, v229, v230
	s_waitcnt lgkmcnt(0)
	v_mfma_f32_32x32x16_bf16 v[20:35], v[202:205], v[198:201], v[20:35]
	v_mov_b32_e32 v3, v2
	v_mfma_f32_32x32x16_bf16 v[4:19], v[214:217], v[198:201], v[4:19]
	ds_read_b64_tr_b16 v[202:203], v197 offset:34816
	ds_read_b64_tr_b16 v[204:205], v197 offset:35840
	ds_read_b64_tr_b16 v[214:215], v218 offset:34816
	ds_read_b64_tr_b16 v[216:217], v218 offset:35840
	v_cvt_pk_bf16_f32 v198, v222, v206
	v_cvt_pk_bf16_f32 v199, v207, v213
	v_cvt_pk_bf16_f32 v200, v223, v224
	v_cvt_pk_bf16_f32 v201, v225, v226
	s_waitcnt lgkmcnt(0)
	s_nop 0
	v_mfma_f32_32x32x16_bf16 v[20:35], v[202:205], v[198:201], v[20:35]
	v_mfma_f32_32x32x16_bf16 v[4:19], v[214:217], v[198:201], v[4:19]
	ds_read_b64_tr_b16 v[198:199], v197 offset:36864
	ds_read_b64_tr_b16 v[200:201], v197 offset:37888
	ds_read_b64_tr_b16 v[202:203], v218 offset:36864
	ds_read_b64_tr_b16 v[204:205], v218 offset:37888
	s_waitcnt lgkmcnt(0)
	v_mfma_f32_32x32x16_bf16 v[20:35], v[198:201], v[0:3], v[20:35]
	v_mfma_f32_32x32x16_bf16 v[4:19], v[202:205], v[0:3], v[4:19]

; template <int A0, int A1, int B0, int B1, bool LOC> ...
;     ...
;     const float mn = fmaxf(m, mx);
;     if (__any(mn > m)) { const float alpha = __builtin_amdgcn_exp2f(m - mn); lsum *= alpha;
; #pragma unroll
;         for (int i = 0; i < 16; ++i) { o0[i] *= alpha; o1[i] *= alpha; } }
;     m = mn;
.LBB0_500:
	v_mov_b32_e32 v143, v195
	v_mov_b32_e32 v141, v196

; #define LAS __attribute__((address_space(3)))
; __device__ __forceinline__ float lane_xor(float v, int lane, int o) { return __int_as_float(__builtin_amdgcn_ds_bpermute((lane ^ o) << 2, __float_as_int(v))); }
; template <int A0, int A1, int B0, int B1, bool LOC> ...
;     if (LOC) {
; #pragma unroll
;         for (int i = A0; i < A1; ++i) s0[i] += sbp[8 * (i >> 2) + (i & 3)] + mk0[i];
; #pragma unroll
;         for (int i = B0; i < B1; ++i) s1v[i] += sbp[32 + 8 * (i >> 2) + (i & 3)] + mk1[i];
;     }
;     float mx = -1e30f;
; #pragma unroll
;     for (int i = A0; i < A1; ++i) mx = fmaxf(mx, s0[i]);
; #pragma unroll
;     for (int i = B0; i < B1; ++i) mx = fmaxf(mx, s1v[i]);
;     mx = fmaxf(mx, lane_xor(mx, lane, 32));
;     const float mn = fmaxf(m, mx);
;     if (__any(mn > m)) { const float alpha = __builtin_amdgcn_exp2f(m - mn); lsum *= alpha;
; #pragma unroll
;         for (int i = 0; i < 16; ++i) { o0[i] *= alpha; o1[i] *= alpha; } }
; __device__ __forceinline__ void attn_blk(bool ctx_too, const bf16_t* U, bf16_t* Y, const float* nb_l, LAS unsigned char* lds, int lane, int wave, int tid) {
;     ...
;                 for (int kk = 0; kk < 4; ++kk) { const int co = ((2 * kk + hh) ^ ksw) << 4;
;                     const bf16x8 k0 = *(const LAS bf16x8*)(kbuf + kro + co), k1 = *(const LAS bf16x8*)(kbuf + 4096 + kro + co);
;                     s0 = __builtin_amdgcn_mfma_f32_32x32x16_bf16(k0, qf[kk], s0, 0, 0, 0); s1v = __builtin_amdgcn_mfma_f32_32x32x16_bf16(k1, qf[kk], s1v, 0, 0, 0); }
;                 if (st < 4) att_soft_pv<0, 16, 0, 16, false>(s0, s1v, o0, o1, m, lsum, vbuf, vro, vsw, lane, sb, mk0, mk1);
;                 else { const LAS float* sbp = sb + 64 + (h * 15 + (j - r + 7)) * 31 + 4 * hh - c + 15;
;                     if (half == 0) att_soft_pv<0, 16, 0, 4, true>(s0, s1v, o0, o1, m, lsum, vbuf, vro, vsw, lane, sbp, mk0, mk1);
;                     else att_soft_pv<12, 16, 0, 16, true>(s0, s1v, o0, o1, m, lsum, vbuf, vro, vsw, lane, sbp, mk0, mk1); }
.LBB0_507:
	v_add_u32_e32 v0, v181, v188
	ds_read_b128 v[36:39], v0 offset:24576
	ds_read_b128 v[40:43], v0 offset:28672
	v_add_u32_e32 v0, v181, v189
	ds_read_b128 v[68:71], v0 offset:24576
	ds_read_b128 v[72:75], v0 offset:28672
	v_add_u32_e32 v0, v181, v190
	s_waitcnt lgkmcnt(0)
	v_mfma_f32_32x32x16_bf16 v[52:67], v[36:39], v[100:103], 0
	s_mov_b64 s[28:29], -1
	s_and_b64 vcc, exec, s[26:27]
	v_mfma_f32_32x32x16_bf16 v[36:51], v[40:43], v[100:103], 0
	v_mfma_f32_32x32x16_bf16 v[52:67], v[68:71], v[104:107], v[52:67]
	v_mfma_f32_32x32x16_bf16 v[36:51], v[72:75], v[104:107], v[36:51]
	ds_read_b128 v[68:71], v0 offset:24576
	ds_read_b128 v[72:75], v0 offset:28672
	v_add_u32_e32 v0, v181, v191
	s_waitcnt lgkmcnt(0)
	v_mfma_f32_32x32x16_bf16 v[52:67], v[68:71], v[108:111], v[52:67]
	v_mfma_f32_32x32x16_bf16 v[36:51], v[72:75], v[108:111], v[36:51]
	ds_read_b128 v[68:71], v0 offset:24576
	ds_read_b128 v[72:75], v0 offset:28672
	s_waitcnt lgkmcnt(0)
	v_mfma_f32_32x32x16_bf16 v[52:67], v[68:71], v[112:115], v[52:67]
	v_mfma_f32_32x32x16_bf16 v[36:51], v[72:75], v[112:115], v[36:51]
	s_cbranch_vccz .LBB0_520
	s_and_b64 vcc, exec, s[4:5]
	s_cbranch_vccz .LBB0_515
	ds_read2_b32 v[0:1], v139 offset0:55 offset1:56
	ds_read2_b32 v[68:69], v139 offset0:57 offset1:58
	ds_read2_b32 v[70:71], v139 offset0:63 offset1:64
	ds_read2_b32 v[72:73], v139 offset0:65 offset1:66
	s_waitcnt lgkmcnt(0)
	v_add_f32_e32 v0, v172, v0
	s_nop 0
	v_add_f32_e32 v218, v64, v0
	v_add_f32_e32 v0, v176, v68
	v_add_f32_e32 v216, v66, v0
	v_add_f32_e32 v0, v178, v69
	v_add_f32_e32 v215, v67, v0
	v_add_f32_e32 v0, v149, v70
	v_add_f32_e32 v214, v36, v0
	v_add_f32_e32 v0, v151, v71
	v_add_f32_e32 v1, v174, v1
	v_add_f32_e32 v213, v37, v0
	v_add_f32_e32 v0, v153, v72
	v_add_f32_e32 v217, v65, v1
	v_add_f32_e32 v206, v38, v0
	ds_read2_b32 v[0:1], v139 offset0:71 offset1:72
	v_add_f32_e32 v3, v155, v73
	ds_read2_b32 v[68:69], v139 offset0:73 offset1:74
	ds_read2_b32 v[70:71], v139 offset0:79 offset1:80
	ds_read2_b32 v[72:73], v139 offset0:81 offset1:82
	v_add_f32_e32 v205, v39, v3
	v_mov_b32_e32 v202, v141
	s_waitcnt lgkmcnt(0)
	v_add_f32_e32 v0, v157, v0
	v_add_f32_e32 v207, v40, v0
	v_add_f32_e32 v0, v159, v1
	v_add_f32_e32 v204, v41, v0
	v_add_f32_e32 v0, v161, v68
	v_add_f32_e32 v203, v42, v0
	v_add_f32_e32 v0, v163, v69
	ds_read2_b32 v[68:69], v139 offset0:87 offset1:88
	v_add_f32_e32 v201, v43, v0
	v_add_f32_e32 v0, v165, v70
	v_add_f32_e32 v200, v44, v0
	v_add_f32_e32 v0, v167, v71
	ds_read2_b32 v[70:71], v139 offset0:89 offset1:90
	s_waitcnt lgkmcnt(0)
	v_add_f32_e32 v68, v173, v68
	v_add_f32_e32 v199, v48, v68
	v_add_f32_e32 v68, v175, v69
	v_add_f32_e32 v198, v49, v68
	v_add_f32_e32 v68, v177, v70
	v_add_f32_e32 v197, v50, v68
	v_add_f32_e32 v68, v179, v71
	v_add_f32_e32 v196, v51, v68
	v_max3_f32 v68, v218, s41, v217
	v_max3_f32 v68, v68, v216, v215
	v_max3_f32 v68, v68, v214, v213
	v_max3_f32 v68, v68, v206, v205
	v_add_f32_e32 v1, v169, v72
	v_max3_f32 v68, v68, v207, v204
	v_add_f32_e32 v0, v45, v0
	v_add_f32_e32 v3, v46, v1
	v_add_f32_e32 v1, v171, v73
	v_max3_f32 v68, v68, v203, v201
	v_add_f32_e32 v1, v47, v1
	v_max3_f32 v68, v68, v200, v0
	v_max3_f32 v68, v68, v3, v1
	v_max3_f32 v68, v68, v199, v198
	v_max3_f32 v68, v68, v197, v196
	ds_bpermute_b32 v69, v182, v68
	s_waitcnt lgkmcnt(0)
	v_max3_f32 v195, v143, v68, v69
	v_cmp_gt_f32_e32 vcc, v195, v143
	s_cbranch_vccz .LBB0_511
	v_sub_f32_e32 v68, v143, v195
	v_exp_f32_e32 v84, v68
	s_nop 0
	v_mul_f32_e32 v202, v141, v84
	v_pk_mul_f32 v[34:35], v[34:35], v[84:85] op_sel_hi:[1,0]
	v_pk_mul_f32 v[32:33], v[32:33], v[84:85] op_sel_hi:[1,0]
	v_pk_mul_f32 v[30:31], v[30:31], v[84:85] op_sel_hi:[1,0]
	v_pk_mul_f32 v[28:29], v[28:29], v[84:85] op_sel_hi:[1,0]
	v_pk_mul_f32 v[26:27], v[26:27], v[84:85] op_sel_hi:[1,0]
	v_pk_mul_f32 v[24:25], v[24:25], v[84:85] op_sel_hi:[1,0]
	v_pk_mul_f32 v[22:23], v[22:23], v[84:85] op_sel_hi:[1,0]
	v_pk_mul_f32 v[20:21], v[20:21], v[84:85] op_sel_hi:[1,0]
	v_pk_mul_f32 v[18:19], v[18:19], v[84:85] op_sel_hi:[1,0]
	v_pk_mul_f32 v[16:17], v[16:17], v[84:85] op_sel_hi:[1,0]
	v_pk_mul_f32 v[14:15], v[14:15], v[84:85] op_sel_hi:[1,0]
	v_pk_mul_f32 v[12:13], v[12:13], v[84:85] op_sel_hi:[1,0]
	v_pk_mul_f32 v[10:11], v[10:11], v[84:85] op_sel_hi:[1,0]
	v_pk_mul_f32 v[8:9], v[8:9], v[84:85] op_sel_hi:[1,0]
	v_pk_mul_f32 v[6:7], v[6:7], v[84:85] op_sel_hi:[1,0]
	v_pk_mul_f32 v[4:5], v[4:5], v[84:85] op_sel_hi:[1,0]
; __device__ __forceinline__ unsigned pk2(float lo, float hi) { const f32x2_t v = {lo, hi}; return __builtin_bit_cast(unsigned, __builtin_convertvector(v, bf16x2_t)); }
; template <int A0, int A1, int B0, int B1, bool LOC> ...
;     ...
;     m = mn;
;     float ps = 0.f;
; #pragma unroll
;     for (int i = 0; i < 16; ++i) { if (i >= A0 && i < A1) { s0[i] = __builtin_amdgcn_exp2f(s0[i] - mn); ps += s0[i]; } else s0[i] = 0.f; }
; #pragma unroll
;     for (int i = 0; i < 16; ++i) { if (i >= B0 && i < B1) { s1v[i] = __builtin_amdgcn_exp2f(s1v[i] - mn); ps += s1v[i]; } else s1v[i] = 0.f; }
;     lsum += ps;
; #pragma unroll
;     for (int kk = 0; kk < 4; ++kk) {
;         const int o = 8 * (kk & 1); const bool live = (kk < 2) ? (o < A1 && o + 8 > A0) : (o < B1 && o + 8 > B0);
;         if (!live) continue;
;         u32x4 pw;
;         if (kk < 2) { pw.x = pk2(s0[o], s0[o + 1]); pw.y = pk2(s0[o + 2], s0[o + 3]); pw.z = pk2(s0[o + 4], s0[o + 5]); pw.w = pk2(s0[o + 6], s0[o + 7]); }
;         else { pw.x = pk2(s1v[o], s1v[o + 1]); pw.y = pk2(s1v[o + 2], s1v[o + 3]); pw.z = pk2(s1v[o + 4], s1v[o + 5]); pw.w = pk2(s1v[o + 6], s1v[o + 7]); }
;         const bf16x8 pf = __builtin_bit_cast(bf16x8, pw);
;         const bf16x8 v0 = tr2(vbuf + kk * 2048 + vro + ((0 ^ vsw) * 64), 1024), v1 = tr2(vbuf + kk * 2048 + vro + ((1 ^ vsw) * 64), 1024);
;         o0 = __builtin_amdgcn_mfma_f32_32x32x16_bf16(v0, pf, o0, 0, 0, 0);
;         o1 = __builtin_amdgcn_mfma_f32_32x32x16_bf16(v1, pf, o1, 0, 0, 0);
;     }
.LBB0_511:
	v_sub_f32_e32 v218, v218, v195
	v_exp_f32_e32 v218, v218
	v_sub_f32_e32 v217, v217, v195
	v_exp_f32_e32 v217, v217
	v_sub_f32_e32 v216, v216, v195
	v_exp_f32_e32 v216, v216
	v_sub_f32_e32 v215, v215, v195
	v_exp_f32_e32 v215, v215
	v_sub_f32_e32 v214, v214, v195
	v_add_f32_e32 v219, 0, v218
	v_exp_f32_e32 v220, v214
	v_add_f32_e32 v219, v217, v219
	v_sub_f32_e32 v213, v213, v195
	v_add_f32_e32 v219, v216, v219
	v_exp_f32_e32 v213, v213
	v_sub_f32_e32 v206, v206, v195
	v_add_f32_e32 v219, v215, v219
	v_exp_f32_e32 v206, v206
	v_sub_f32_e32 v205, v205, v195
	v_add_f32_e32 v214, v220, v219
	v_exp_f32_e32 v219, v205
	v_sub_f32_e32 v207, v207, v195
	v_exp_f32_e32 v207, v207
	v_sub_f32_e32 v204, v204, v195
	v_add_f32_e32 v214, v213, v214
	v_exp_f32_e32 v221, v204
	v_sub_f32_e32 v203, v203, v195
	v_add_f32_e32 v214, v206, v214
	v_exp_f32_e32 v222, v203
	v_sub_f32_e32 v201, v201, v195
	v_add_f32_e32 v205, v219, v214
	v_exp_f32_e32 v223, v201
	v_sub_f32_e32 v200, v200, v195
	v_add_f32_e32 v205, v207, v205
	v_exp_f32_e32 v224, v200
	v_sub_f32_e32 v0, v0, v195
	v_add_f32_e32 v204, v221, v205
	v_exp_f32_e32 v0, v0
	v_sub_f32_e32 v3, v3, v195
	v_add_f32_e32 v203, v222, v204
	v_exp_f32_e32 v3, v3
	v_sub_f32_e32 v1, v1, v195
	v_add_f32_e32 v201, v223, v203
	v_exp_f32_e32 v1, v1
	v_sub_f32_e32 v199, v199, v195
	v_add_f32_e32 v200, v224, v201
	v_exp_f32_e32 v225, v199
	v_sub_f32_e32 v198, v198, v195
	v_add_f32_e32 v200, v0, v200
	v_exp_f32_e32 v226, v198
	v_sub_f32_e32 v197, v197, v195
	v_add_f32_e32 v200, v3, v200
	v_exp_f32_e32 v197, v197
	v_sub_f32_e32 v196, v196, v195
	v_add_f32_e32 v200, v1, v200
	v_exp_f32_e32 v227, v196
	v_add_f32_e32 v199, v225, v200
	v_add_f32_e32 v198, v226, v199
	v_add_f32_e32 v198, v197, v198
	v_add_f32_e32 v196, v227, v198
	v_cvt_pk_bf16_f32 v200, v218, v217
	v_add_u32_e32 v218, v183, v184
	v_add_u32_e32 v228, v183, v185
	v_add_f32_e32 v196, v196, v202
	v_cvt_pk_bf16_f32 v201, v216, v215
	ds_read_b64_tr_b16 v[202:203], v218 offset:43008
	ds_read_b64_tr_b16 v[204:205], v218 offset:44032
	ds_read_b64_tr_b16 v[214:215], v228 offset:43008
	ds_read_b64_tr_b16 v[216:217], v228 offset:44032
	v_mov_b32_e32 v198, v2
	v_mov_b32_e32 v199, v2
	s_waitcnt lgkmcnt(0)
	s_nop 0
	v_mfma_f32_32x32x16_bf16 v[20:35], v[202:205], v[198:201], v[20:35]
	v_mfma_f32_32x32x16_bf16 v[4:19], v[214:217], v[198:201], v[4:19]
	ds_read_b64_tr_b16 v[202:203], v218 offset:45056
	ds_read_b64_tr_b16 v[204:205], v218 offset:46080
	ds_read_b64_tr_b16 v[214:215], v228 offset:45056
	ds_read_b64_tr_b16 v[216:217], v228 offset:46080
	v_cvt_pk_bf16_f32 v198, v220, v213
	v_cvt_pk_bf16_f32 v199, v206, v219
	v_cvt_pk_bf16_f32 v200, v207, v221
	v_cvt_pk_bf16_f32 v201, v222, v223
	s_waitcnt lgkmcnt(0)
	s_nop 0
	v_mfma_f32_32x32x16_bf16 v[20:35], v[202:205], v[198:201], v[20:35]
	v_mfma_f32_32x32x16_bf16 v[4:19], v[214:217], v[198:201], v[4:19]
	ds_read_b64_tr_b16 v[202:203], v218 offset:47104
	ds_read_b64_tr_b16 v[204:205], v218 offset:48128
	ds_read_b64_tr_b16 v[214:215], v228 offset:47104
	ds_read_b64_tr_b16 v[216:217], v228 offset:48128
	v_cvt_pk_bf16_f32 v198, v224, v0
	v_cvt_pk_bf16_f32 v199, v3, v1
	v_cvt_pk_bf16_f32 v200, v225, v226
	v_cvt_pk_bf16_f32 v201, v197, v227
	s_waitcnt lgkmcnt(0)
	s_nop 0
	v_mfma_f32_32x32x16_bf16 v[20:35], v[202:205], v[198:201], v[20:35]
	v_mfma_f32_32x32x16_bf16 v[4:19], v[214:217], v[198:201], v[4:19]
	s_branch .LBB0_519

; __device__ __forceinline__ unsigned pk2(float lo, float hi) { const f32x2_t v = {lo, hi}; return __builtin_bit_cast(unsigned, __builtin_convertvector(v, bf16x2_t)); }
; __device__ __forceinline__ float lane_xor(float v, int lane, int o) { return __int_as_float(__builtin_amdgcn_ds_bpermute((lane ^ o) << 2, __float_as_int(v))); }
; template <int A0, int A1, int B0, int B1, bool LOC> ...
;     if (LOC) {
; #pragma unroll
;         for (int i = A0; i < A1; ++i) s0[i] += sbp[8 * (i >> 2) + (i & 3)] + mk0[i];
; #pragma unroll
;         for (int i = B0; i < B1; ++i) s1v[i] += sbp[32 + 8 * (i >> 2) + (i & 3)] + mk1[i];
;     }
;     float mx = -1e30f;
; #pragma unroll
;     for (int i = A0; i < A1; ++i) mx = fmaxf(mx, s0[i]);
; #pragma unroll
;     for (int i = B0; i < B1; ++i) mx = fmaxf(mx, s1v[i]);
;     mx = fmaxf(mx, lane_xor(mx, lane, 32));
;     const float mn = fmaxf(m, mx);
;     if (__any(mn > m)) { const float alpha = __builtin_amdgcn_exp2f(m - mn); lsum *= alpha;
; #pragma unroll
;         for (int i = 0; i < 16; ++i) { o0[i] *= alpha; o1[i] *= alpha; } }
;     m = mn;
;     float ps = 0.f;
; #pragma unroll
;     for (int i = 0; i < 16; ++i) { if (i >= A0 && i < A1) { s0[i] = __builtin_amdgcn_exp2f(s0[i] - mn); ps += s0[i]; } else s0[i] = 0.f; }
; #pragma unroll
;     for (int i = 0; i < 16; ++i) { if (i >= B0 && i < B1) { s1v[i] = __builtin_amdgcn_exp2f(s1v[i] - mn); ps += s1v[i]; } else s1v[i] = 0.f; }
;     lsum += ps;
; #pragma unroll
;     for (int kk = 0; kk < 4; ++kk) {
;         const int o = 8 * (kk & 1); const bool live = (kk < 2) ? (o < A1 && o + 8 > A0) : (o < B1 && o + 8 > B0);
;         if (!live) continue;
;         u32x4 pw;
;         if (kk < 2) { pw.x = pk2(s0[o], s0[o + 1]); pw.y = pk2(s0[o + 2], s0[o + 3]); pw.z = pk2(s0[o + 4], s0[o + 5]); pw.w = pk2(s0[o + 6], s0[o + 7]); }
;         else { pw.x = pk2(s1v[o], s1v[o + 1]); pw.y = pk2(s1v[o + 2], s1v[o + 3]); pw.z = pk2(s1v[o + 4], s1v[o + 5]); pw.w = pk2(s1v[o + 6], s1v[o + 7]); }
;         const bf16x8 pf = __builtin_bit_cast(bf16x8, pw);
;         const bf16x8 v0 = tr2(vbuf + kk * 2048 + vro + ((0 ^ vsw) * 64), 1024), v1 = tr2(vbuf + kk * 2048 + vro + ((1 ^ vsw) * 64), 1024);
;         o0 = __builtin_amdgcn_mfma_f32_32x32x16_bf16(v0, pf, o0, 0, 0, 0);
;         o1 = __builtin_amdgcn_mfma_f32_32x32x16_bf16(v1, pf, o1, 0, 0, 0);
;     }
.LBB0_515:
	s_cbranch_execz .LBB0_519
	ds_read2_b32 v[0:1], v139 offset0:31 offset1:32
	ds_read2_b32 v[68:69], v139 offset0:33 offset1:34
	ds_read2_b32 v[70:71], v139 offset0:39 offset1:40
	ds_read2_b32 v[72:73], v139 offset0:41 offset1:42
	s_waitcnt lgkmcnt(0)
	v_add_f32_e32 v0, v148, v0
	v_add_f32_e32 v1, v150, v1
	v_add_f32_e32 v199, v52, v0
	v_add_f32_e32 v0, v53, v1
	v_add_f32_e32 v1, v152, v68
	v_add_f32_e32 v68, v156, v70
	v_add_f32_e32 v196, v56, v68
	v_add_f32_e32 v68, v158, v71
	v_add_f32_e32 v197, v57, v68
	v_add_f32_e32 v68, v160, v72
	v_add_f32_e32 v3, v154, v69
	v_add_f32_e32 v198, v58, v68
	ds_read2_b32 v[68:69], v139 offset0:47 offset1:48
	v_add_f32_e32 v70, v162, v73
	v_add_f32_e32 v200, v59, v70
	ds_read2_b32 v[70:71], v139 offset0:49 offset1:50
	ds_read2_b32 v[72:73], v139 offset0:55 offset1:56
	ds_read2_b32 v[74:75], v139 offset0:57 offset1:58
	v_add_f32_e32 v1, v54, v1
	s_waitcnt lgkmcnt(0)
	v_add_f32_e32 v68, v164, v68
	v_add_f32_e32 v205, v60, v68
	v_add_f32_e32 v68, v166, v69
	v_add_f32_e32 v206, v61, v68
	v_add_f32_e32 v68, v168, v70
	v_add_f32_e32 v207, v62, v68
	v_add_f32_e32 v68, v170, v71
	v_add_f32_e32 v213, v63, v68
	v_add_f32_e32 v68, v172, v72
	v_add_f32_e32 v214, v64, v68
	v_add_f32_e32 v68, v174, v73
	v_add_f32_e32 v215, v65, v68
	v_add_f32_e32 v70, v176, v74
	ds_read2_b32 v[68:69], v139 offset0:63 offset1:64
	v_add_f32_e32 v216, v66, v70
	v_add_f32_e32 v70, v178, v75
	v_add_f32_e32 v217, v67, v70
	ds_read2_b32 v[70:71], v139 offset0:65 offset1:66
	s_waitcnt lgkmcnt(0)
	v_add_f32_e32 v68, v149, v68
	v_add_f32_e32 v204, v36, v68
	v_add_f32_e32 v68, v151, v69
	v_add_f32_e32 v203, v37, v68
	v_add_f32_e32 v68, v153, v70
	v_add_f32_e32 v202, v38, v68
	v_add_f32_e32 v68, v155, v71
	v_add_f32_e32 v3, v55, v3
	v_add_f32_e32 v201, v39, v68
	v_max3_f32 v68, v199, s41, v0
	v_max3_f32 v68, v68, v1, v3
	v_max3_f32 v68, v68, v196, v197
	v_max3_f32 v68, v68, v198, v200
	v_max3_f32 v68, v68, v205, v206
	v_max3_f32 v68, v68, v207, v213
	v_max3_f32 v68, v68, v214, v215
	v_max3_f32 v68, v68, v216, v217
	v_max3_f32 v68, v68, v204, v203
	v_max3_f32 v68, v68, v202, v201
	ds_bpermute_b32 v69, v182, v68
	v_mov_b32_e32 v218, v141
	s_waitcnt lgkmcnt(0)
	v_max3_f32 v195, v143, v68, v69
	v_cmp_gt_f32_e32 vcc, v195, v143
	s_cbranch_vccz .LBB0_518
	v_sub_f32_e32 v68, v143, v195
	v_exp_f32_e32 v84, v68
	s_nop 0
	v_mul_f32_e32 v218, v141, v84
	v_pk_mul_f32 v[34:35], v[34:35], v[84:85] op_sel_hi:[1,0]
	v_pk_mul_f32 v[32:33], v[32:33], v[84:85] op_sel_hi:[1,0]
	v_pk_mul_f32 v[30:31], v[30:31], v[84:85] op_sel_hi:[1,0]
	v_pk_mul_f32 v[28:29], v[28:29], v[84:85] op_sel_hi:[1,0]
	v_pk_mul_f32 v[26:27], v[26:27], v[84:85] op_sel_hi:[1,0]
	v_pk_mul_f32 v[24:25], v[24:25], v[84:85] op_sel_hi:[1,0]
	v_pk_mul_f32 v[22:23], v[22:23], v[84:85] op_sel_hi:[1,0]
	v_pk_mul_f32 v[20:21], v[20:21], v[84:85] op_sel_hi:[1,0]
	v_pk_mul_f32 v[18:19], v[18:19], v[84:85] op_sel_hi:[1,0]
	v_pk_mul_f32 v[16:17], v[16:17], v[84:85] op_sel_hi:[1,0]
	v_pk_mul_f32 v[14:15], v[14:15], v[84:85] op_sel_hi:[1,0]
	v_pk_mul_f32 v[12:13], v[12:13], v[84:85] op_sel_hi:[1,0]
	v_pk_mul_f32 v[10:11], v[10:11], v[84:85] op_sel_hi:[1,0]
	v_pk_mul_f32 v[8:9], v[8:9], v[84:85] op_sel_hi:[1,0]
	v_pk_mul_f32 v[6:7], v[6:7], v[84:85] op_sel_hi:[1,0]
	v_pk_mul_f32 v[4:5], v[4:5], v[84:85] op_sel_hi:[1,0]
.LBB0_518:
	v_sub_f32_e32 v196, v196, v195
	v_exp_f32_e32 v219, v196
	v_sub_f32_e32 v196, v197, v195
	v_exp_f32_e32 v197, v196
	v_sub_f32_e32 v196, v198, v195
	v_exp_f32_e32 v220, v196
	v_sub_f32_e32 v196, v200, v195
	v_exp_f32_e32 v221, v196
	v_sub_f32_e32 v196, v205, v195
	v_exp_f32_e32 v222, v196
	v_sub_f32_e32 v196, v206, v195
	v_exp_f32_e32 v206, v196
	v_sub_f32_e32 v196, v207, v195
	v_sub_f32_e32 v199, v199, v195
	v_exp_f32_e32 v207, v196
	v_sub_f32_e32 v196, v213, v195
	v_exp_f32_e32 v199, v199
	v_sub_f32_e32 v0, v0, v195
	v_exp_f32_e32 v213, v196
	v_sub_f32_e32 v196, v214, v195
	v_exp_f32_e32 v0, v0
	v_sub_f32_e32 v1, v1, v195
	v_exp_f32_e32 v223, v196
	v_sub_f32_e32 v196, v215, v195
	v_exp_f32_e32 v1, v1
	v_sub_f32_e32 v3, v3, v195
	v_exp_f32_e32 v224, v196
	v_sub_f32_e32 v196, v216, v195
	v_exp_f32_e32 v3, v3
	v_exp_f32_e32 v225, v196
	v_sub_f32_e32 v196, v217, v195
	v_exp_f32_e32 v226, v196
	v_add_f32_e32 v196, 0, v199
	v_add_f32_e32 v196, v0, v196
	v_add_f32_e32 v196, v1, v196
	v_add_f32_e32 v196, v3, v196
	v_add_f32_e32 v196, v219, v196
	v_add_f32_e32 v196, v197, v196
	v_add_f32_e32 v196, v220, v196
	v_add_f32_e32 v196, v221, v196
	v_add_f32_e32 v196, v222, v196
	v_add_f32_e32 v196, v206, v196
	v_add_f32_e32 v196, v207, v196
	v_add_f32_e32 v196, v213, v196
	v_sub_f32_e32 v198, v204, v195
	v_add_f32_e32 v196, v223, v196
	v_exp_f32_e32 v227, v198
	v_sub_f32_e32 v198, v203, v195
	v_add_f32_e32 v196, v224, v196
	v_exp_f32_e32 v228, v198
	v_sub_f32_e32 v198, v202, v195
	v_add_f32_e32 v196, v225, v196
	v_exp_f32_e32 v229, v198
	v_sub_f32_e32 v198, v201, v195
	v_add_f32_e32 v196, v226, v196
	v_exp_f32_e32 v230, v198
	v_add_f32_e32 v196, v227, v196
	v_add_f32_e32 v196, v228, v196
	v_add_f32_e32 v196, v229, v196
	v_add_f32_e32 v196, v230, v196
	v_add_f32_e32 v196, v196, v218
	v_cvt_pk_bf16_f32 v200, v219, v197
	v_add_u32_e32 v197, v183, v184
	v_add_u32_e32 v218, v183, v185
	ds_read_b64_tr_b16 v[202:203], v197 offset:40960
	ds_read_b64_tr_b16 v[204:205], v197 offset:41984
	ds_read_b64_tr_b16 v[214:215], v218 offset:40960
	ds_read_b64_tr_b16 v[216:217], v218 offset:41984
	v_cvt_pk_bf16_f32 v198, v199, v0
	v_cvt_pk_bf16_f32 v199, v1, v3
	v_cvt_pk_bf16_f32 v201, v220, v221
	v_cvt_pk_bf16_f32 v0, v227, v228
	v_cvt_pk_bf16_f32 v1, v229, v230
	s_waitcnt lgkmcnt(0)
	v_mfma_f32_32x32x16_bf16 v[20:35], v[202:205], v[198:201], v[20:35]
	v_mov_b32_e32 v3, v2
	v_mfma_f32_32x32x16_bf16 v[4:19], v[214:217], v[198:201], v[4:19]
	ds_read_b64_tr_b16 v[202:203], v197 offset:43008
	ds_read_b64_tr_b16 v[204:205], v197 offset:44032
	ds_read_b64_tr_b16 v[214:215], v218 offset:43008
	ds_read_b64_tr_b16 v[216:217], v218 offset:44032
	v_cvt_pk_bf16_f32 v198, v222, v206
	v_cvt_pk_bf16_f32 v199, v207, v213
	v_cvt_pk_bf16_f32 v200, v223, v224
	v_cvt_pk_bf16_f32 v201, v225, v226
	s_waitcnt lgkmcnt(0)
	s_nop 0
	v_mfma_f32_32x32x16_bf16 v[20:35], v[202:205], v[198:201], v[20:35]
	v_mfma_f32_32x32x16_bf16 v[4:19], v[214:217], v[198:201], v[4:19]
	ds_read_b64_tr_b16 v[198:199], v197 offset:45056
	ds_read_b64_tr_b16 v[200:201], v197 offset:46080
	ds_read_b64_tr_b16 v[202:203], v218 offset:45056
	ds_read_b64_tr_b16 v[204:205], v218 offset:46080
	s_waitcnt lgkmcnt(0)
	v_mfma_f32_32x32x16_bf16 v[20:35], v[198:201], v[0:3], v[20:35]
	v_mfma_f32_32x32x16_bf16 v[4:19], v[202:205], v[0:3], v[4:19]

; template <int A0, int A1, int B0, int B1, bool LOC> ...
;     ...
;     const float mn = fmaxf(m, mx);
;     if (__any(mn > m)) { const float alpha = __builtin_amdgcn_exp2f(m - mn); lsum *= alpha;
; #pragma unroll
;         for (int i = 0; i < 16; ++i) { o0[i] *= alpha; o1[i] *= alpha; } }
;     m = mn;
.LBB0_524:
	v_mov_b32_e32 v143, v195
	v_mov_b32_e32 v141, v196
	s_andn2_b64 vcc, exec, s[6:7]
	s_cbranch_vccnz .LBB0_479

; #define LAS __attribute__((address_space(3)))
; #define LDS_WAIT() asm volatile("s_waitcnt lgkmcnt(0)" ::: "memory")
; __device__ __forceinline__ void stage_z(const bf16_t* U, int tok0, int stride, int col_r, int col_i, LAS unsigned char* tile, int lane) {
;     ...
;     for (int it = 0; it < 16; ++it) { const int idx = it * 64 + lane, row = idx >> 3, piece = (idx >> 2) & 1, chunk = idx & 3;
;         v[it] = *(const u32x4*)(U + (size_t)(tok0 + stride * row) * NU + (piece ? col_i : col_r) + 8 * chunk); }
; #pragma unroll
;     for (int it = 0; it < 16; ++it) { const int idx = it * 64 + lane, row = idx >> 3, piece = (idx >> 2) & 1, chunk = idx & 3;
;         *(LAS u32x4*)(tile + row * 128 + ((piece ^ ((row >> 1) & 1)) * 64) + chunk * 16) = v[it]; }
; __device__ __forceinline__ void dft1_mfma(const bf16_t* U, bf16_t* YB, const bf16_t* A1, const float* TW, LAS unsigned char* tile, int gw, int NGW, int lane) {
;     ...
;     for (int u = gw; u < 2048; u += NGW) {
;         const int nh = u & 1, g = (u >> 1) & 3, sf = (u >> 3) & 63, b = u >> 9;
;         stage_z(U, b * SEQ + sf, 64, UC_Z + 128 * g + 32 * nh, UC_Z + 128 * g + 64 + 32 * nh, tile, lane);
;         LDS_WAIT();
; #pragma unroll
;         for (int mb = 0; mb < 4; ++mb) {
;             f32x16 aR, aI;
; #pragma unroll
;             for (int i = 0; i < 16; ++i) { aR[i] = 0.f; aI[i] = 0.f; }
;             const bf16_t* ap = A1 + (size_t)(32 * mb + r32) * 256 + 8 * hh;
; #pragma unroll
;             for (int kk = 0; kk < 8; ++kk) {
;                 const bf16x8 ac = *(const bf16x8*)(ap + 16 * kk), as = *(const bf16x8*)(ap + 128 + 16 * kk);
;                 const bf16x8 br = tr2(tile + offR + kk * 2048, 512), bi = tr2(tile + offI + kk * 2048, 512);
.LBB0_697:
	s_and_b32 s3, s15, 0x180
	s_and_b32 s6, s13, 32
	v_add_u32_e32 v4, s3, v80
	s_bfe_u32 s18, s10, 0x60003
	s_and_b32 s0, s2, 0xffffe000
	v_or_b32_e32 v4, s6, v4
	s_or_b32 s17, s0, s18
	v_lshlrev_b32_e32 v4, 1, v4
	v_mov_b32_e32 v5, v2
	v_lshl_add_u64 v[172:173], v[0:1], 0, v[4:5]
	v_or_b32_e32 v75, s17, v3
	v_mad_i64_i32 v[4:5], s[0:1], v75, s50, v[172:173]
	v_or_b32_e32 v8, 0x200, v75
	global_load_dwordx4 v[4:7], v[4:5], off
	v_mad_i64_i32 v[8:9], s[0:1], v8, s50, v[172:173]
	v_or_b32_e32 v12, 0x400, v75
	global_load_dwordx4 v[8:11], v[8:9], off
	v_mad_i64_i32 v[12:13], s[0:1], v12, s50, v[172:173]
	v_or_b32_e32 v16, 0x600, v75
	global_load_dwordx4 v[12:15], v[12:13], off
	v_mad_i64_i32 v[16:17], s[0:1], v16, s50, v[172:173]
	v_or_b32_e32 v20, 0x800, v75
	global_load_dwordx4 v[16:19], v[16:17], off
	v_mad_i64_i32 v[20:21], s[0:1], v20, s50, v[172:173]
	v_or_b32_e32 v24, 0xa00, v75
	global_load_dwordx4 v[20:23], v[20:21], off
	v_mad_i64_i32 v[24:25], s[0:1], v24, s50, v[172:173]
	v_or_b32_e32 v28, 0xc00, v75
	global_load_dwordx4 v[24:27], v[24:25], off
	v_mad_i64_i32 v[28:29], s[0:1], v28, s50, v[172:173]
	v_or_b32_e32 v32, 0xe00, v75
	global_load_dwordx4 v[28:31], v[28:29], off
	v_mad_i64_i32 v[32:33], s[0:1], v32, s50, v[172:173]
	v_or_b32_e32 v76, 0x1000, v75
	global_load_dwordx4 v[32:35], v[32:33], off
	v_mad_i64_i32 v[76:77], s[0:1], v76, s50, v[172:173]
	v_or_b32_e32 v148, 0x1200, v75
	global_load_dwordx4 v[76:79], v[76:77], off
	v_mad_i64_i32 v[148:149], s[0:1], v148, s50, v[172:173]
	v_or_b32_e32 v152, 0x1400, v75
	global_load_dwordx4 v[148:151], v[148:149], off
	v_mad_i64_i32 v[152:153], s[0:1], v152, s50, v[172:173]
	v_or_b32_e32 v156, 0x1600, v75
	global_load_dwordx4 v[152:155], v[152:153], off
	v_mad_i64_i32 v[156:157], s[0:1], v156, s50, v[172:173]
	v_or_b32_e32 v160, 0x1800, v75
	global_load_dwordx4 v[156:159], v[156:157], off
	v_mad_i64_i32 v[160:161], s[0:1], v160, s50, v[172:173]
	v_or_b32_e32 v164, 0x1a00, v75
	global_load_dwordx4 v[160:163], v[160:161], off
	v_mad_i64_i32 v[164:165], s[0:1], v164, s50, v[172:173]
	v_or_b32_e32 v168, 0x1c00, v75
	global_load_dwordx4 v[164:167], v[164:165], off
	v_mad_i64_i32 v[168:169], s[0:1], v168, s50, v[172:173]
	v_or_b32_e32 v75, 0x1e00, v75
	global_load_dwordx4 v[168:171], v[168:169], off
	v_mad_i64_i32 v[172:173], s[0:1], v75, s50, v[172:173]
	global_load_dwordx4 v[172:175], v[172:173], off
	s_lshl_b32 s0, s3, 1
	s_add_u32 s0, s20, s0
	s_addc_u32 s1, s21, 0
	s_lshl_b32 s3, s6, 1
	s_add_u32 s6, s0, s3
	s_addc_u32 s7, s1, 0
	v_mov_b32_e32 v75, v2
	s_add_i32 s10, s10, s12
	s_add_i32 s13, s13, s14
	s_add_i32 s15, s15, s11
	s_add_i32 s2, s2, s16
	s_cmpk_gt_i32 s10, 0x7ff
	s_waitcnt vmcnt(0) lgkmcnt(0)
	ds_write_b128 v145, v[4:7]
	ds_write_b128 v145, v[8:11] offset:1024
	ds_write_b128 v145, v[12:15] offset:2048
	ds_write_b128 v145, v[16:19] offset:3072
	ds_write_b128 v145, v[20:23] offset:4096
	ds_write_b128 v145, v[24:27] offset:5120
	ds_write_b128 v145, v[28:31] offset:6144
	ds_write_b128 v145, v[32:35] offset:7168
	ds_write_b128 v145, v[76:79] offset:8192
	ds_write_b128 v145, v[148:151] offset:9216
	ds_write_b128 v145, v[152:155] offset:10240
	ds_write_b128 v145, v[156:159] offset:11264
	ds_write_b128 v145, v[160:163] offset:12288
	ds_write_b128 v145, v[164:167] offset:13312
	ds_write_b128 v145, v[168:171] offset:14336
	ds_write_b128 v145, v[172:175] offset:15360
	s_waitcnt lgkmcnt(0)
	v_or_b32_e32 v229, s18, v81
	v_lshlrev_b32_e32 v229, 2, v229
	global_load_dwordx4 v[84:87], v[36:37], off
	global_load_dwordx4 v[88:91], v[36:37], off offset:256
	global_load_dwordx4 v[92:95], v[36:37], off offset:32
	global_load_dwordx4 v[96:99], v[36:37], off offset:288
	global_load_dwordx4 v[100:103], v[36:37], off offset:64
	global_load_dwordx4 v[104:107], v[36:37], off offset:320
	global_load_dwordx4 v[108:111], v[36:37], off offset:96
	global_load_dwordx4 v[112:115], v[36:37], off offset:352
	global_load_dwordx4 v[116:119], v[36:37], off offset:128
	global_load_dwordx4 v[120:123], v[36:37], off offset:384
	global_load_dwordx4 v[124:127], v[36:37], off offset:160
	global_load_dwordx4 v[128:131], v[36:37], off offset:416
	global_load_dwordx4 v[132:135], v[36:37], off offset:192
	global_load_dwordx4 v[136:139], v[36:37], off offset:448
	global_load_dwordx4 v[140:143], v[36:37], off offset:224
	global_load_dwordx4 v[60:63], v[36:37], off offset:480
	v_or_b32_e32 v231, 0x0, v229
	v_add_u32_e32 v232, 0x8000, v231
	global_load_dword v42, v231, s[4:5]
	global_load_dword v213, v232, s[4:5]
	v_or_b32_e32 v231, 0x100, v229
	v_add_u32_e32 v232, 0x8000, v231
	global_load_dword v43, v231, s[4:5]
	global_load_dword v214, v232, s[4:5]
	v_or_b32_e32 v231, 0x200, v229
	v_add_u32_e32 v232, 0x8000, v231
	global_load_dword v44, v231, s[4:5]
	global_load_dword v215, v232, s[4:5]
	v_or_b32_e32 v231, 0x300, v229
	v_add_u32_e32 v232, 0x8000, v231
	global_load_dword v45, v231, s[4:5]
	global_load_dword v216, v232, s[4:5]
	v_or_b32_e32 v231, 0x800, v229
	v_add_u32_e32 v232, 0x8000, v231
	global_load_dword v46, v231, s[4:5]
	global_load_dword v217, v232, s[4:5]
	v_or_b32_e32 v231, 0x900, v229
	v_add_u32_e32 v232, 0x8000, v231
	global_load_dword v47, v231, s[4:5]
	global_load_dword v218, v232, s[4:5]
	v_or_b32_e32 v231, 0xa00, v229
	v_add_u32_e32 v232, 0x8000, v231
	global_load_dword v48, v231, s[4:5]
	global_load_dword v219, v232, s[4:5]
	v_or_b32_e32 v231, 0xb00, v229
	v_add_u32_e32 v232, 0x8000, v231
	global_load_dword v49, v231, s[4:5]
	global_load_dword v220, v232, s[4:5]
	v_or_b32_e32 v231, 0x1000, v229
	v_add_u32_e32 v232, 0x8000, v231
	global_load_dword v50, v231, s[4:5]
	global_load_dword v221, v232, s[4:5]
; __device__ __forceinline__ void dft1_mfma(const bf16_t* U, bf16_t* YB, const bf16_t* A1, const float* TW, LAS unsigned char* tile, int gw, int NGW, int lane) {
;     ...
;             for (int kk = 0; kk < 8; ++kk) {
;                 const bf16x8 ac = *(const bf16x8*)(ap + 16 * kk), as = *(const bf16x8*)(ap + 128 + 16 * kk);
;                 const bf16x8 br = tr2(tile + offR + kk * 2048, 512), bi = tr2(tile + offI + kk * 2048, 512);
;                 aR = __builtin_amdgcn_mfma_f32_32x32x16_bf16(ac, br, aR, 0, 0, 0); aR = __builtin_amdgcn_mfma_f32_32x32x16_bf16(as, bi, aR, 0, 0, 0);
;                 aI = __builtin_amdgcn_mfma_f32_32x32x16_bf16(ac, bi, aI, 0, 0, 0); aI = __builtin_amdgcn_mfma_f32_32x32x16_bf16(negbf(as), br, aI, 0, 0, 0);
;             }
; #pragma unroll
;             for (int i = 0; i < 16; ++i) { const int ka = 32 * mb + 8 * (i >> 2) + 4 * hh + (i & 3); const float tc = TW[ka * 64 + sf], ts = TW[8192 + ka * 64 + sf];
	v_or_b32_e32 v231, 0x1100, v229
	v_add_u32_e32 v232, 0x8000, v231
	global_load_dword v51, v231, s[4:5]
	global_load_dword v222, v232, s[4:5]
	v_or_b32_e32 v231, 0x1200, v229
	v_add_u32_e32 v232, 0x8000, v231
	global_load_dword v52, v231, s[4:5]
	global_load_dword v223, v232, s[4:5]
	v_or_b32_e32 v231, 0x1300, v229
	v_add_u32_e32 v232, 0x8000, v231
	global_load_dword v53, v231, s[4:5]
	global_load_dword v224, v232, s[4:5]
	v_or_b32_e32 v231, 0x1800, v229
	v_add_u32_e32 v232, 0x8000, v231
	global_load_dword v54, v231, s[4:5]
	global_load_dword v225, v232, s[4:5]
	v_or_b32_e32 v231, 0x1900, v229
	v_add_u32_e32 v232, 0x8000, v231
	global_load_dword v55, v231, s[4:5]
	global_load_dword v226, v232, s[4:5]
	v_or_b32_e32 v231, 0x1a00, v229
	v_add_u32_e32 v232, 0x8000, v231
	global_load_dword v56, v231, s[4:5]
	global_load_dword v227, v232, s[4:5]
	v_or_b32_e32 v231, 0x1b00, v229
	v_add_u32_e32 v232, 0x8000, v231
	global_load_dword v57, v231, s[4:5]
	global_load_dword v228, v232, s[4:5]
	ds_read_b64_tr_b16 v[148:149], v146
	ds_read_b64_tr_b16 v[150:151], v146 offset:512
	ds_read_b64_tr_b16 v[152:153], v147
	ds_read_b64_tr_b16 v[154:155], v147 offset:512
	ds_read_b64_tr_b16 v[156:157], v146 offset:2048
	ds_read_b64_tr_b16 v[158:159], v146 offset:2560
	ds_read_b64_tr_b16 v[160:161], v147 offset:2048
	ds_read_b64_tr_b16 v[162:163], v147 offset:2560
	ds_read_b64_tr_b16 v[164:165], v146 offset:4096
	ds_read_b64_tr_b16 v[166:167], v146 offset:4608
	ds_read_b64_tr_b16 v[168:169], v147 offset:4096
	ds_read_b64_tr_b16 v[170:171], v147 offset:4608
	ds_read_b64_tr_b16 v[172:173], v146 offset:6144
	ds_read_b64_tr_b16 v[174:175], v146 offset:6656
	ds_read_b64_tr_b16 v[176:177], v147 offset:6144
	ds_read_b64_tr_b16 v[178:179], v147 offset:6656
	ds_read_b64_tr_b16 v[180:181], v146 offset:8192
	ds_read_b64_tr_b16 v[182:183], v146 offset:8704
	ds_read_b64_tr_b16 v[184:185], v147 offset:8192
	ds_read_b64_tr_b16 v[186:187], v147 offset:8704
	ds_read_b64_tr_b16 v[188:189], v146 offset:10240
	ds_read_b64_tr_b16 v[190:191], v146 offset:10752
	ds_read_b64_tr_b16 v[192:193], v147 offset:10240
	ds_read_b64_tr_b16 v[194:195], v147 offset:10752
	ds_read_b64_tr_b16 v[196:197], v146 offset:12288
	ds_read_b64_tr_b16 v[198:199], v146 offset:12800
	ds_read_b64_tr_b16 v[200:201], v147 offset:12288
	ds_read_b64_tr_b16 v[202:203], v147 offset:12800
	ds_read_b64_tr_b16 v[204:205], v146 offset:14336
	ds_read_b64_tr_b16 v[206:207], v146 offset:14848
	ds_read_b64_tr_b16 v[64:65], v147 offset:14336
	ds_read_b64_tr_b16 v[66:67], v147 offset:14848
	v_lshlrev_b32_e64 v237, 14, s74
	v_lshlrev_b32_e32 v239, 4, v249
	v_add_u32_e32 v239, v237, v239
	v_and_b32_e32 v231, 32, v249
	v_lshlrev_b32_e32 v231, 4, v231
	v_add3_u32 v237, v237, v231, v74
	v_lshlrev_b32_e64 v233, 10, s17
	v_lshrrev_b32_e32 v231, 3, v249
	v_lshl_add_u32 v233, v231, 16, v233
	v_and_b32_e32 v231, 7, v249
	v_lshl_add_u32 v233, v231, 4, v233
	v_and_b32_e32 v231, 4, v249
	v_lshl_add_u32 v233, v231, 4, v233
	s_waitcnt lgkmcnt(0)
	s_waitcnt vmcnt(32)
	v_mfma_f32_32x32x16_bf16 v[4:19], v[84:87], v[148:151], 0
	v_mfma_f32_32x32x16_bf16 v[4:19], v[88:91], v[152:155], v[4:19]
	v_xor_b32_e32 v68, 0x80008000, v88
	v_xor_b32_e32 v69, 0x80008000, v89
	v_xor_b32_e32 v70, 0x80008000, v90
	v_xor_b32_e32 v71, 0x80008000, v91
	v_mfma_f32_32x32x16_bf16 v[20:35], v[84:87], v[152:155], 0
	s_nop 0
	v_mfma_f32_32x32x16_bf16 v[20:35], v[68:71], v[148:151], v[20:35]
	v_mfma_f32_32x32x16_bf16 v[4:19], v[92:95], v[156:159], v[4:19]
	v_mfma_f32_32x32x16_bf16 v[4:19], v[96:99], v[160:163], v[4:19]
	v_xor_b32_e32 v68, 0x80008000, v96
	v_xor_b32_e32 v69, 0x80008000, v97
	v_xor_b32_e32 v70, 0x80008000, v98
	v_xor_b32_e32 v71, 0x80008000, v99
	v_mfma_f32_32x32x16_bf16 v[20:35], v[92:95], v[160:163], v[20:35]
	s_nop 0
	v_mfma_f32_32x32x16_bf16 v[20:35], v[68:71], v[156:159], v[20:35]
	v_mfma_f32_32x32x16_bf16 v[4:19], v[100:103], v[164:167], v[4:19]
	v_mfma_f32_32x32x16_bf16 v[4:19], v[104:107], v[168:171], v[4:19]
	v_xor_b32_e32 v68, 0x80008000, v104
	v_xor_b32_e32 v69, 0x80008000, v105
	v_xor_b32_e32 v70, 0x80008000, v106
	v_xor_b32_e32 v71, 0x80008000, v107
	v_mfma_f32_32x32x16_bf16 v[20:35], v[100:103], v[168:171], v[20:35]
	s_nop 0
	v_mfma_f32_32x32x16_bf16 v[20:35], v[68:71], v[164:167], v[20:35]
	v_mfma_f32_32x32x16_bf16 v[4:19], v[108:111], v[172:175], v[4:19]
	v_mfma_f32_32x32x16_bf16 v[4:19], v[112:115], v[176:179], v[4:19]
	v_xor_b32_e32 v68, 0x80008000, v112
	v_xor_b32_e32 v69, 0x80008000, v113
	v_xor_b32_e32 v70, 0x80008000, v114
	v_xor_b32_e32 v71, 0x80008000, v115
	v_mfma_f32_32x32x16_bf16 v[20:35], v[108:111], v[176:179], v[20:35]
	s_nop 0
	v_mfma_f32_32x32x16_bf16 v[20:35], v[68:71], v[172:175], v[20:35]
	v_mfma_f32_32x32x16_bf16 v[4:19], v[116:119], v[180:183], v[4:19]
	v_mfma_f32_32x32x16_bf16 v[4:19], v[120:123], v[184:187], v[4:19]
	v_xor_b32_e32 v68, 0x80008000, v120
	v_xor_b32_e32 v69, 0x80008000, v121
	v_xor_b32_e32 v70, 0x80008000, v122
	v_xor_b32_e32 v71, 0x80008000, v123
	v_mfma_f32_32x32x16_bf16 v[20:35], v[116:119], v[184:187], v[20:35]
	s_nop 0
	v_mfma_f32_32x32x16_bf16 v[20:35], v[68:71], v[180:183], v[20:35]
	v_mfma_f32_32x32x16_bf16 v[4:19], v[124:127], v[188:191], v[4:19]
	v_mfma_f32_32x32x16_bf16 v[4:19], v[128:131], v[192:195], v[4:19]
	v_xor_b32_e32 v68, 0x80008000, v128
	v_xor_b32_e32 v69, 0x80008000, v129
	v_xor_b32_e32 v70, 0x80008000, v130
	v_xor_b32_e32 v71, 0x80008000, v131
	v_mfma_f32_32x32x16_bf16 v[20:35], v[124:127], v[192:195], v[20:35]
	s_nop 0
	v_mfma_f32_32x32x16_bf16 v[20:35], v[68:71], v[188:191], v[20:35]
	v_mfma_f32_32x32x16_bf16 v[4:19], v[132:135], v[196:199], v[4:19]
; __device__ __forceinline__ bf16_t bf1(float v) { return (bf16_t)pk2(v, 0.f); }
; __device__ __forceinline__ void dft1_mfma(const bf16_t* U, bf16_t* YB, const bf16_t* A1, const float* TW, LAS unsigned char* tile, int gw, int NGW, int lane) {
;     ...
;             for (int kk = 0; kk < 8; ++kk) {
;                 const bf16x8 ac = *(const bf16x8*)(ap + 16 * kk), as = *(const bf16x8*)(ap + 128 + 16 * kk);
;                 const bf16x8 br = tr2(tile + offR + kk * 2048, 512), bi = tr2(tile + offI + kk * 2048, 512);
;                 aR = __builtin_amdgcn_mfma_f32_32x32x16_bf16(ac, br, aR, 0, 0, 0); aR = __builtin_amdgcn_mfma_f32_32x32x16_bf16(as, bi, aR, 0, 0, 0);
;                 aI = __builtin_amdgcn_mfma_f32_32x32x16_bf16(ac, bi, aI, 0, 0, 0); aI = __builtin_amdgcn_mfma_f32_32x32x16_bf16(negbf(as), br, aI, 0, 0, 0);
;             }
; #pragma unroll
;             for (int i = 0; i < 16; ++i) { const int ka = 32 * mb + 8 * (i >> 2) + 4 * hh + (i & 3); const float tc = TW[ka * 64 + sf], ts = TW[8192 + ka * 64 + sf];
;                 const float r2 = tc * aR[i] + ts * aI[i], i2 = tc * aI[i] - ts * aR[i]; bf16_t* op = YB + (size_t)(b * SEQ + ka * 64 + sf) * 512 + 128 * g + 32 * nh + r32;
;                 op[0] = bf1(r2); op[64] = bf1(i2); }
	v_mfma_f32_32x32x16_bf16 v[4:19], v[136:139], v[200:203], v[4:19]
	v_xor_b32_e32 v68, 0x80008000, v136
	v_xor_b32_e32 v69, 0x80008000, v137
	v_xor_b32_e32 v70, 0x80008000, v138
	v_xor_b32_e32 v71, 0x80008000, v139
	v_mfma_f32_32x32x16_bf16 v[20:35], v[132:135], v[200:203], v[20:35]
	s_nop 0
	v_mfma_f32_32x32x16_bf16 v[20:35], v[68:71], v[196:199], v[20:35]
	v_mfma_f32_32x32x16_bf16 v[4:19], v[140:143], v[204:207], v[4:19]
	v_mfma_f32_32x32x16_bf16 v[4:19], v[60:63], v[64:67], v[4:19]
	v_xor_b32_e32 v68, 0x80008000, v60
	v_xor_b32_e32 v69, 0x80008000, v61
	v_xor_b32_e32 v70, 0x80008000, v62
	v_xor_b32_e32 v71, 0x80008000, v63
	v_mfma_f32_32x32x16_bf16 v[20:35], v[140:143], v[64:67], v[20:35]
	s_nop 0
	v_mfma_f32_32x32x16_bf16 v[20:35], v[68:71], v[204:207], v[20:35]
	global_load_dwordx4 v[84:87], v[38:39], off
	global_load_dwordx4 v[88:91], v[38:39], off offset:256
	global_load_dwordx4 v[92:95], v[38:39], off offset:32
	global_load_dwordx4 v[96:99], v[38:39], off offset:288
	global_load_dwordx4 v[100:103], v[38:39], off offset:64
	global_load_dwordx4 v[104:107], v[38:39], off offset:320
	global_load_dwordx4 v[108:111], v[38:39], off offset:96
	global_load_dwordx4 v[112:115], v[38:39], off offset:352
	global_load_dwordx4 v[116:119], v[38:39], off offset:128
	global_load_dwordx4 v[120:123], v[38:39], off offset:384
	global_load_dwordx4 v[124:127], v[38:39], off offset:160
	global_load_dwordx4 v[128:131], v[38:39], off offset:416
	global_load_dwordx4 v[132:135], v[38:39], off offset:192
	global_load_dwordx4 v[136:139], v[38:39], off offset:448
	global_load_dwordx4 v[140:143], v[38:39], off offset:224
	global_load_dwordx4 v[60:63], v[38:39], off offset:480
	s_waitcnt vmcnt(16)
	s_nop 15
	v_mul_f32_e32 v235, v20, v213
	v_mul_f32_e32 v236, v4, v213
	v_fmac_f32_e32 v235, v4, v42
	v_fma_f32 v236, v20, v42, -v236
	v_cvt_pk_bf16_f32 v235, v235, v235
	v_cvt_pk_bf16_f32 v236, v236, v236
	ds_write_b16 v237, v235 offset:0
	ds_write_b16 v237, v236 offset:64
	v_mul_f32_e32 v235, v21, v214
	v_mul_f32_e32 v236, v5, v214
	v_fmac_f32_e32 v235, v5, v43
	v_fma_f32 v236, v21, v43, -v236
	v_cvt_pk_bf16_f32 v235, v235, v235
	v_cvt_pk_bf16_f32 v236, v236, v236
	ds_write_b16 v237, v235 offset:128
	ds_write_b16 v237, v236 offset:192
	v_mul_f32_e32 v235, v22, v215
	v_mul_f32_e32 v236, v6, v215
	v_fmac_f32_e32 v235, v6, v44
	v_fma_f32 v236, v22, v44, -v236
	v_cvt_pk_bf16_f32 v235, v235, v235
	v_cvt_pk_bf16_f32 v236, v236, v236
	ds_write_b16 v237, v235 offset:256
	ds_write_b16 v237, v236 offset:320
	v_mul_f32_e32 v235, v23, v216
	v_mul_f32_e32 v236, v7, v216
	v_fmac_f32_e32 v235, v7, v45
	v_fma_f32 v236, v23, v45, -v236
	v_cvt_pk_bf16_f32 v235, v235, v235
	v_cvt_pk_bf16_f32 v236, v236, v236
	ds_write_b16 v237, v235 offset:384
	ds_write_b16 v237, v236 offset:448
	v_mul_f32_e32 v235, v24, v217
	v_mul_f32_e32 v236, v8, v217
	v_fmac_f32_e32 v235, v8, v46
	v_fma_f32 v236, v24, v46, -v236
	v_cvt_pk_bf16_f32 v235, v235, v235
	v_cvt_pk_bf16_f32 v236, v236, v236
	ds_write_b16 v237, v235 offset:1024
	ds_write_b16 v237, v236 offset:1088
	v_mul_f32_e32 v235, v25, v218
	v_mul_f32_e32 v236, v9, v218
	v_fmac_f32_e32 v235, v9, v47
	v_fma_f32 v236, v25, v47, -v236
	v_cvt_pk_bf16_f32 v235, v235, v235
	v_cvt_pk_bf16_f32 v236, v236, v236
	ds_write_b16 v237, v235 offset:1152
	ds_write_b16 v237, v236 offset:1216
	v_mul_f32_e32 v235, v26, v219
	v_mul_f32_e32 v236, v10, v219
	v_fmac_f32_e32 v235, v10, v48
	v_fma_f32 v236, v26, v48, -v236
	v_cvt_pk_bf16_f32 v235, v235, v235
	v_cvt_pk_bf16_f32 v236, v236, v236
	ds_write_b16 v237, v235 offset:1280
	ds_write_b16 v237, v236 offset:1344
	v_mul_f32_e32 v235, v27, v220
	v_mul_f32_e32 v236, v11, v220
	v_fmac_f32_e32 v235, v11, v49
	v_fma_f32 v236, v27, v49, -v236
	v_cvt_pk_bf16_f32 v235, v235, v235
	v_cvt_pk_bf16_f32 v236, v236, v236
	ds_write_b16 v237, v235 offset:1408
	ds_write_b16 v237, v236 offset:1472
	v_mul_f32_e32 v235, v28, v221
	v_mul_f32_e32 v236, v12, v221
	v_fmac_f32_e32 v235, v12, v50
	v_fma_f32 v236, v28, v50, -v236
	v_cvt_pk_bf16_f32 v235, v235, v235
	v_cvt_pk_bf16_f32 v236, v236, v236
	ds_write_b16 v237, v235 offset:2048
	ds_write_b16 v237, v236 offset:2112
	v_mul_f32_e32 v235, v29, v222
	v_mul_f32_e32 v236, v13, v222
	v_fmac_f32_e32 v235, v13, v51
	v_fma_f32 v236, v29, v51, -v236
	v_cvt_pk_bf16_f32 v235, v235, v235
	v_cvt_pk_bf16_f32 v236, v236, v236
	ds_write_b16 v237, v235 offset:2176
	ds_write_b16 v237, v236 offset:2240
	v_mul_f32_e32 v235, v30, v223
	v_mul_f32_e32 v236, v14, v223
	v_fmac_f32_e32 v235, v14, v52
	v_fma_f32 v236, v30, v52, -v236
	v_cvt_pk_bf16_f32 v235, v235, v235
	v_cvt_pk_bf16_f32 v236, v236, v236
	ds_write_b16 v237, v235 offset:2304
	ds_write_b16 v237, v236 offset:2368
	v_mul_f32_e32 v235, v31, v224
	v_mul_f32_e32 v236, v15, v224
	v_fmac_f32_e32 v235, v15, v53
	v_fma_f32 v236, v31, v53, -v236
	v_cvt_pk_bf16_f32 v235, v235, v235
	v_cvt_pk_bf16_f32 v236, v236, v236
	ds_write_b16 v237, v235 offset:2432
	ds_write_b16 v237, v236 offset:2496
	v_mul_f32_e32 v235, v32, v225
	v_mul_f32_e32 v236, v16, v225
	v_fmac_f32_e32 v235, v16, v54
	v_fma_f32 v236, v32, v54, -v236
	v_cvt_pk_bf16_f32 v235, v235, v235
	v_cvt_pk_bf16_f32 v236, v236, v236
	ds_write_b16 v237, v235 offset:3072
	ds_write_b16 v237, v236 offset:3136
	v_mul_f32_e32 v235, v33, v226
	v_mul_f32_e32 v236, v17, v226
	v_fmac_f32_e32 v235, v17, v55
	v_fma_f32 v236, v33, v55, -v236
	v_cvt_pk_bf16_f32 v235, v235, v235
	v_cvt_pk_bf16_f32 v236, v236, v236
	ds_write_b16 v237, v235 offset:3200
	ds_write_b16 v237, v236 offset:3264
	v_mul_f32_e32 v235, v34, v227
	v_mul_f32_e32 v236, v18, v227
	v_fmac_f32_e32 v235, v18, v56
	v_fma_f32 v236, v34, v56, -v236
; __device__ __forceinline__ bf16_t bf1(float v) { return (bf16_t)pk2(v, 0.f); }
; __device__ __forceinline__ void dft1_mfma(const bf16_t* U, bf16_t* YB, const bf16_t* A1, const float* TW, LAS unsigned char* tile, int gw, int NGW, int lane) {
;     ...
;             for (int kk = 0; kk < 8; ++kk) {
;                 const bf16x8 ac = *(const bf16x8*)(ap + 16 * kk), as = *(const bf16x8*)(ap + 128 + 16 * kk);
;                 const bf16x8 br = tr2(tile + offR + kk * 2048, 512), bi = tr2(tile + offI + kk * 2048, 512);
;                 aR = __builtin_amdgcn_mfma_f32_32x32x16_bf16(ac, br, aR, 0, 0, 0); aR = __builtin_amdgcn_mfma_f32_32x32x16_bf16(as, bi, aR, 0, 0, 0);
;                 aI = __builtin_amdgcn_mfma_f32_32x32x16_bf16(ac, bi, aI, 0, 0, 0); aI = __builtin_amdgcn_mfma_f32_32x32x16_bf16(negbf(as), br, aI, 0, 0, 0);
;             }
; #pragma unroll
;             for (int i = 0; i < 16; ++i) { const int ka = 32 * mb + 8 * (i >> 2) + 4 * hh + (i & 3); const float tc = TW[ka * 64 + sf], ts = TW[8192 + ka * 64 + sf];
;                 const float r2 = tc * aR[i] + ts * aI[i], i2 = tc * aI[i] - ts * aR[i]; bf16_t* op = YB + (size_t)(b * SEQ + ka * 64 + sf) * 512 + 128 * g + 32 * nh + r32;
;                 op[0] = bf1(r2); op[64] = bf1(i2); }
	v_cvt_pk_bf16_f32 v235, v235, v235
	v_cvt_pk_bf16_f32 v236, v236, v236
	ds_write_b16 v237, v235 offset:3328
	ds_write_b16 v237, v236 offset:3392
	v_mul_f32_e32 v235, v35, v228
	v_mul_f32_e32 v236, v19, v228
	v_fmac_f32_e32 v235, v19, v57
	v_fma_f32 v236, v35, v57, -v236
	v_cvt_pk_bf16_f32 v235, v235, v235
	v_cvt_pk_bf16_f32 v236, v236, v236
	ds_write_b16 v237, v235 offset:3456
	ds_write_b16 v237, v236 offset:3520
	v_or_b32_e32 v231, 0x2000, v229
	v_add_u32_e32 v232, 0x8000, v231
	global_load_dword v42, v231, s[4:5]
	global_load_dword v213, v232, s[4:5]
	v_or_b32_e32 v231, 0x2100, v229
	v_add_u32_e32 v232, 0x8000, v231
	global_load_dword v43, v231, s[4:5]
	global_load_dword v214, v232, s[4:5]
	v_or_b32_e32 v231, 0x2200, v229
	v_add_u32_e32 v232, 0x8000, v231
	global_load_dword v44, v231, s[4:5]
	global_load_dword v215, v232, s[4:5]
	v_or_b32_e32 v231, 0x2300, v229
	v_add_u32_e32 v232, 0x8000, v231
	global_load_dword v45, v231, s[4:5]
	global_load_dword v216, v232, s[4:5]
	v_or_b32_e32 v231, 0x2800, v229
	v_add_u32_e32 v232, 0x8000, v231
	global_load_dword v46, v231, s[4:5]
	global_load_dword v217, v232, s[4:5]
	v_or_b32_e32 v231, 0x2900, v229
	v_add_u32_e32 v232, 0x8000, v231
	global_load_dword v47, v231, s[4:5]
	global_load_dword v218, v232, s[4:5]
	v_or_b32_e32 v231, 0x2a00, v229
	v_add_u32_e32 v232, 0x8000, v231
	global_load_dword v48, v231, s[4:5]
	global_load_dword v219, v232, s[4:5]
	v_or_b32_e32 v231, 0x2b00, v229
	v_add_u32_e32 v232, 0x8000, v231
	global_load_dword v49, v231, s[4:5]
	global_load_dword v220, v232, s[4:5]
	v_or_b32_e32 v231, 0x3000, v229
	v_add_u32_e32 v232, 0x8000, v231
	global_load_dword v50, v231, s[4:5]
	global_load_dword v221, v232, s[4:5]
	v_or_b32_e32 v231, 0x3100, v229
	v_add_u32_e32 v232, 0x8000, v231
	global_load_dword v51, v231, s[4:5]
	global_load_dword v222, v232, s[4:5]
	v_or_b32_e32 v231, 0x3200, v229
	v_add_u32_e32 v232, 0x8000, v231
	global_load_dword v52, v231, s[4:5]
	global_load_dword v223, v232, s[4:5]
	v_or_b32_e32 v231, 0x3300, v229
	v_add_u32_e32 v232, 0x8000, v231
	global_load_dword v53, v231, s[4:5]
	global_load_dword v224, v232, s[4:5]
	v_or_b32_e32 v231, 0x3800, v229
	v_add_u32_e32 v232, 0x8000, v231
	global_load_dword v54, v231, s[4:5]
	global_load_dword v225, v232, s[4:5]
	v_or_b32_e32 v231, 0x3900, v229
	v_add_u32_e32 v232, 0x8000, v231
	global_load_dword v55, v231, s[4:5]
	global_load_dword v226, v232, s[4:5]
	v_or_b32_e32 v231, 0x3a00, v229
	v_add_u32_e32 v232, 0x8000, v231
	global_load_dword v56, v231, s[4:5]
	global_load_dword v227, v232, s[4:5]
	v_or_b32_e32 v231, 0x3b00, v229
	v_add_u32_e32 v232, 0x8000, v231
	global_load_dword v57, v231, s[4:5]
	global_load_dword v228, v232, s[4:5]
	s_waitcnt lgkmcnt(0)
	ds_read_b128 v[76:79], v239 offset:0
	ds_read_b128 v[244:247], v239 offset:1024
	ds_read_b128 v[250:253], v239 offset:2048
	ds_read_b128 v[240:243], v239 offset:3072
	s_waitcnt lgkmcnt(3)
	v_add_u32_e32 v234, 0x0, v233
	global_store_dwordx4 v234, v[76:79], s[6:7]
	s_waitcnt lgkmcnt(2)
	v_add_u32_e32 v234, 0x80000, v233
	global_store_dwordx4 v234, v[244:247], s[6:7]
	s_waitcnt lgkmcnt(1)
	v_add_u32_e32 v234, 0x100000, v233
	global_store_dwordx4 v234, v[250:253], s[6:7]
	s_waitcnt lgkmcnt(0)
	v_add_u32_e32 v234, 0x180000, v233
	global_store_dwordx4 v234, v[240:243], s[6:7]
	s_waitcnt vmcnt(32)
	v_mfma_f32_32x32x16_bf16 v[4:19], v[84:87], v[148:151], 0
	v_mfma_f32_32x32x16_bf16 v[4:19], v[88:91], v[152:155], v[4:19]
	v_xor_b32_e32 v68, 0x80008000, v88
	v_xor_b32_e32 v69, 0x80008000, v89
	v_xor_b32_e32 v70, 0x80008000, v90
	v_xor_b32_e32 v71, 0x80008000, v91
	v_mfma_f32_32x32x16_bf16 v[20:35], v[84:87], v[152:155], 0
	s_nop 0
	v_mfma_f32_32x32x16_bf16 v[20:35], v[68:71], v[148:151], v[20:35]
	v_mfma_f32_32x32x16_bf16 v[4:19], v[92:95], v[156:159], v[4:19]
	v_mfma_f32_32x32x16_bf16 v[4:19], v[96:99], v[160:163], v[4:19]
	v_xor_b32_e32 v68, 0x80008000, v96
	v_xor_b32_e32 v69, 0x80008000, v97
	v_xor_b32_e32 v70, 0x80008000, v98
	v_xor_b32_e32 v71, 0x80008000, v99
	v_mfma_f32_32x32x16_bf16 v[20:35], v[92:95], v[160:163], v[20:35]
	s_nop 0
	v_mfma_f32_32x32x16_bf16 v[20:35], v[68:71], v[156:159], v[20:35]
	v_mfma_f32_32x32x16_bf16 v[4:19], v[100:103], v[164:167], v[4:19]
	v_mfma_f32_32x32x16_bf16 v[4:19], v[104:107], v[168:171], v[4:19]
	v_xor_b32_e32 v68, 0x80008000, v104
	v_xor_b32_e32 v69, 0x80008000, v105
	v_xor_b32_e32 v70, 0x80008000, v106
	v_xor_b32_e32 v71, 0x80008000, v107
	v_mfma_f32_32x32x16_bf16 v[20:35], v[100:103], v[168:171], v[20:35]
	s_nop 0
	v_mfma_f32_32x32x16_bf16 v[20:35], v[68:71], v[164:167], v[20:35]
	v_mfma_f32_32x32x16_bf16 v[4:19], v[108:111], v[172:175], v[4:19]
	v_mfma_f32_32x32x16_bf16 v[4:19], v[112:115], v[176:179], v[4:19]
	v_xor_b32_e32 v68, 0x80008000, v112
	v_xor_b32_e32 v69, 0x80008000, v113
	v_xor_b32_e32 v70, 0x80008000, v114
	v_xor_b32_e32 v71, 0x80008000, v115
	v_mfma_f32_32x32x16_bf16 v[20:35], v[108:111], v[176:179], v[20:35]
	s_nop 0
	v_mfma_f32_32x32x16_bf16 v[20:35], v[68:71], v[172:175], v[20:35]
	v_mfma_f32_32x32x16_bf16 v[4:19], v[116:119], v[180:183], v[4:19]
	v_mfma_f32_32x32x16_bf16 v[4:19], v[120:123], v[184:187], v[4:19]
	v_xor_b32_e32 v68, 0x80008000, v120
	v_xor_b32_e32 v69, 0x80008000, v121
	v_xor_b32_e32 v70, 0x80008000, v122
	v_xor_b32_e32 v71, 0x80008000, v123
	v_mfma_f32_32x32x16_bf16 v[20:35], v[116:119], v[184:187], v[20:35]
	s_nop 0
	v_mfma_f32_32x32x16_bf16 v[20:35], v[68:71], v[180:183], v[20:35]
	v_mfma_f32_32x32x16_bf16 v[4:19], v[124:127], v[188:191], v[4:19]
	v_mfma_f32_32x32x16_bf16 v[4:19], v[128:131], v[192:195], v[4:19]
	v_xor_b32_e32 v68, 0x80008000, v128
	v_xor_b32_e32 v69, 0x80008000, v129
; __device__ __forceinline__ bf16_t bf1(float v) { return (bf16_t)pk2(v, 0.f); }
; __device__ __forceinline__ void dft1_mfma(const bf16_t* U, bf16_t* YB, const bf16_t* A1, const float* TW, LAS unsigned char* tile, int gw, int NGW, int lane) {
;     ...
;             for (int kk = 0; kk < 8; ++kk) {
;                 const bf16x8 ac = *(const bf16x8*)(ap + 16 * kk), as = *(const bf16x8*)(ap + 128 + 16 * kk);
;                 const bf16x8 br = tr2(tile + offR + kk * 2048, 512), bi = tr2(tile + offI + kk * 2048, 512);
;                 aR = __builtin_amdgcn_mfma_f32_32x32x16_bf16(ac, br, aR, 0, 0, 0); aR = __builtin_amdgcn_mfma_f32_32x32x16_bf16(as, bi, aR, 0, 0, 0);
;                 aI = __builtin_amdgcn_mfma_f32_32x32x16_bf16(ac, bi, aI, 0, 0, 0); aI = __builtin_amdgcn_mfma_f32_32x32x16_bf16(negbf(as), br, aI, 0, 0, 0);
;             }
; #pragma unroll
;             for (int i = 0; i < 16; ++i) { const int ka = 32 * mb + 8 * (i >> 2) + 4 * hh + (i & 3); const float tc = TW[ka * 64 + sf], ts = TW[8192 + ka * 64 + sf];
;                 const float r2 = tc * aR[i] + ts * aI[i], i2 = tc * aI[i] - ts * aR[i]; bf16_t* op = YB + (size_t)(b * SEQ + ka * 64 + sf) * 512 + 128 * g + 32 * nh + r32;
;                 op[0] = bf1(r2); op[64] = bf1(i2); }
	v_xor_b32_e32 v70, 0x80008000, v130
	v_xor_b32_e32 v71, 0x80008000, v131
	v_mfma_f32_32x32x16_bf16 v[20:35], v[124:127], v[192:195], v[20:35]
	s_nop 0
	v_mfma_f32_32x32x16_bf16 v[20:35], v[68:71], v[188:191], v[20:35]
	v_mfma_f32_32x32x16_bf16 v[4:19], v[132:135], v[196:199], v[4:19]
	v_mfma_f32_32x32x16_bf16 v[4:19], v[136:139], v[200:203], v[4:19]
	v_xor_b32_e32 v68, 0x80008000, v136
	v_xor_b32_e32 v69, 0x80008000, v137
	v_xor_b32_e32 v70, 0x80008000, v138
	v_xor_b32_e32 v71, 0x80008000, v139
	v_mfma_f32_32x32x16_bf16 v[20:35], v[132:135], v[200:203], v[20:35]
	s_nop 0
	v_mfma_f32_32x32x16_bf16 v[20:35], v[68:71], v[196:199], v[20:35]
	v_mfma_f32_32x32x16_bf16 v[4:19], v[140:143], v[204:207], v[4:19]
	v_mfma_f32_32x32x16_bf16 v[4:19], v[60:63], v[64:67], v[4:19]
	v_xor_b32_e32 v68, 0x80008000, v60
	v_xor_b32_e32 v69, 0x80008000, v61
	v_xor_b32_e32 v70, 0x80008000, v62
	v_xor_b32_e32 v71, 0x80008000, v63
	v_mfma_f32_32x32x16_bf16 v[20:35], v[140:143], v[64:67], v[20:35]
	s_nop 0
	v_mfma_f32_32x32x16_bf16 v[20:35], v[68:71], v[204:207], v[20:35]
	global_load_dwordx4 v[84:87], v[40:41], off
	global_load_dwordx4 v[88:91], v[40:41], off offset:256
	global_load_dwordx4 v[92:95], v[40:41], off offset:32
	global_load_dwordx4 v[96:99], v[40:41], off offset:288
	global_load_dwordx4 v[100:103], v[40:41], off offset:64
	global_load_dwordx4 v[104:107], v[40:41], off offset:320
	global_load_dwordx4 v[108:111], v[40:41], off offset:96
	global_load_dwordx4 v[112:115], v[40:41], off offset:352
	global_load_dwordx4 v[116:119], v[40:41], off offset:128
	global_load_dwordx4 v[120:123], v[40:41], off offset:384
	global_load_dwordx4 v[124:127], v[40:41], off offset:160
	global_load_dwordx4 v[128:131], v[40:41], off offset:416
	global_load_dwordx4 v[132:135], v[40:41], off offset:192
	global_load_dwordx4 v[136:139], v[40:41], off offset:448
	global_load_dwordx4 v[140:143], v[40:41], off offset:224
	global_load_dwordx4 v[60:63], v[40:41], off offset:480
	s_waitcnt vmcnt(16)
	s_nop 15
	v_mul_f32_e32 v235, v20, v213
	v_mul_f32_e32 v236, v4, v213
	v_fmac_f32_e32 v235, v4, v42
	v_fma_f32 v236, v20, v42, -v236
	v_cvt_pk_bf16_f32 v235, v235, v235
	v_cvt_pk_bf16_f32 v236, v236, v236
	ds_write_b16 v237, v235 offset:4096
	ds_write_b16 v237, v236 offset:4160
	v_mul_f32_e32 v235, v21, v214
	v_mul_f32_e32 v236, v5, v214
	v_fmac_f32_e32 v235, v5, v43
	v_fma_f32 v236, v21, v43, -v236
	v_cvt_pk_bf16_f32 v235, v235, v235
	v_cvt_pk_bf16_f32 v236, v236, v236
	ds_write_b16 v237, v235 offset:4224
	ds_write_b16 v237, v236 offset:4288
	v_mul_f32_e32 v235, v22, v215
	v_mul_f32_e32 v236, v6, v215
	v_fmac_f32_e32 v235, v6, v44
	v_fma_f32 v236, v22, v44, -v236
	v_cvt_pk_bf16_f32 v235, v235, v235
	v_cvt_pk_bf16_f32 v236, v236, v236
	ds_write_b16 v237, v235 offset:4352
	ds_write_b16 v237, v236 offset:4416
	v_mul_f32_e32 v235, v23, v216
	v_mul_f32_e32 v236, v7, v216
	v_fmac_f32_e32 v235, v7, v45
	v_fma_f32 v236, v23, v45, -v236
	v_cvt_pk_bf16_f32 v235, v235, v235
	v_cvt_pk_bf16_f32 v236, v236, v236
	ds_write_b16 v237, v235 offset:4480
	ds_write_b16 v237, v236 offset:4544
	v_mul_f32_e32 v235, v24, v217
	v_mul_f32_e32 v236, v8, v217
	v_fmac_f32_e32 v235, v8, v46
	v_fma_f32 v236, v24, v46, -v236
	v_cvt_pk_bf16_f32 v235, v235, v235
	v_cvt_pk_bf16_f32 v236, v236, v236
	ds_write_b16 v237, v235 offset:5120
	ds_write_b16 v237, v236 offset:5184
	v_mul_f32_e32 v235, v25, v218
	v_mul_f32_e32 v236, v9, v218
	v_fmac_f32_e32 v235, v9, v47
	v_fma_f32 v236, v25, v47, -v236
	v_cvt_pk_bf16_f32 v235, v235, v235
	v_cvt_pk_bf16_f32 v236, v236, v236
	ds_write_b16 v237, v235 offset:5248
	ds_write_b16 v237, v236 offset:5312
	v_mul_f32_e32 v235, v26, v219
	v_mul_f32_e32 v236, v10, v219
	v_fmac_f32_e32 v235, v10, v48
	v_fma_f32 v236, v26, v48, -v236
	v_cvt_pk_bf16_f32 v235, v235, v235
	v_cvt_pk_bf16_f32 v236, v236, v236
	ds_write_b16 v237, v235 offset:5376
	ds_write_b16 v237, v236 offset:5440
	v_mul_f32_e32 v235, v27, v220
	v_mul_f32_e32 v236, v11, v220
	v_fmac_f32_e32 v235, v11, v49
	v_fma_f32 v236, v27, v49, -v236
	v_cvt_pk_bf16_f32 v235, v235, v235
	v_cvt_pk_bf16_f32 v236, v236, v236
	ds_write_b16 v237, v235 offset:5504
	ds_write_b16 v237, v236 offset:5568
	v_mul_f32_e32 v235, v28, v221
	v_mul_f32_e32 v236, v12, v221
	v_fmac_f32_e32 v235, v12, v50
	v_fma_f32 v236, v28, v50, -v236
	v_cvt_pk_bf16_f32 v235, v235, v235
	v_cvt_pk_bf16_f32 v236, v236, v236
	ds_write_b16 v237, v235 offset:6144
	ds_write_b16 v237, v236 offset:6208
	v_mul_f32_e32 v235, v29, v222
	v_mul_f32_e32 v236, v13, v222
	v_fmac_f32_e32 v235, v13, v51
	v_fma_f32 v236, v29, v51, -v236
	v_cvt_pk_bf16_f32 v235, v235, v235
	v_cvt_pk_bf16_f32 v236, v236, v236
	ds_write_b16 v237, v235 offset:6272
	ds_write_b16 v237, v236 offset:6336
	v_mul_f32_e32 v235, v30, v223
	v_mul_f32_e32 v236, v14, v223
	v_fmac_f32_e32 v235, v14, v52
	v_fma_f32 v236, v30, v52, -v236
	v_cvt_pk_bf16_f32 v235, v235, v235
	v_cvt_pk_bf16_f32 v236, v236, v236
	ds_write_b16 v237, v235 offset:6400
	ds_write_b16 v237, v236 offset:6464
	v_mul_f32_e32 v235, v31, v224
	v_mul_f32_e32 v236, v15, v224
	v_fmac_f32_e32 v235, v15, v53
	v_fma_f32 v236, v31, v53, -v236
	v_cvt_pk_bf16_f32 v235, v235, v235
	v_cvt_pk_bf16_f32 v236, v236, v236
	ds_write_b16 v237, v235 offset:6528
	ds_write_b16 v237, v236 offset:6592
	v_mul_f32_e32 v235, v32, v225
	v_mul_f32_e32 v236, v16, v225
	v_fmac_f32_e32 v235, v16, v54
	v_fma_f32 v236, v32, v54, -v236
	v_cvt_pk_bf16_f32 v235, v235, v235
	v_cvt_pk_bf16_f32 v236, v236, v236
	ds_write_b16 v237, v235 offset:7168
	ds_write_b16 v237, v236 offset:7232
	v_mul_f32_e32 v235, v33, v226
	v_mul_f32_e32 v236, v17, v226
	v_fmac_f32_e32 v235, v17, v55
	v_fma_f32 v236, v33, v55, -v236
; __device__ __forceinline__ bf16_t bf1(float v) { return (bf16_t)pk2(v, 0.f); }
; __device__ __forceinline__ void dft1_mfma(const bf16_t* U, bf16_t* YB, const bf16_t* A1, const float* TW, LAS unsigned char* tile, int gw, int NGW, int lane) {
;     ...
;             for (int kk = 0; kk < 8; ++kk) {
;                 const bf16x8 ac = *(const bf16x8*)(ap + 16 * kk), as = *(const bf16x8*)(ap + 128 + 16 * kk);
;                 const bf16x8 br = tr2(tile + offR + kk * 2048, 512), bi = tr2(tile + offI + kk * 2048, 512);
;                 aR = __builtin_amdgcn_mfma_f32_32x32x16_bf16(ac, br, aR, 0, 0, 0); aR = __builtin_amdgcn_mfma_f32_32x32x16_bf16(as, bi, aR, 0, 0, 0);
;                 aI = __builtin_amdgcn_mfma_f32_32x32x16_bf16(ac, bi, aI, 0, 0, 0); aI = __builtin_amdgcn_mfma_f32_32x32x16_bf16(negbf(as), br, aI, 0, 0, 0);
;             }
; #pragma unroll
;             for (int i = 0; i < 16; ++i) { const int ka = 32 * mb + 8 * (i >> 2) + 4 * hh + (i & 3); const float tc = TW[ka * 64 + sf], ts = TW[8192 + ka * 64 + sf];
;                 const float r2 = tc * aR[i] + ts * aI[i], i2 = tc * aI[i] - ts * aR[i]; bf16_t* op = YB + (size_t)(b * SEQ + ka * 64 + sf) * 512 + 128 * g + 32 * nh + r32;
;                 op[0] = bf1(r2); op[64] = bf1(i2); }
	v_cvt_pk_bf16_f32 v235, v235, v235
	v_cvt_pk_bf16_f32 v236, v236, v236
	ds_write_b16 v237, v235 offset:7296
	ds_write_b16 v237, v236 offset:7360
	v_mul_f32_e32 v235, v34, v227
	v_mul_f32_e32 v236, v18, v227
	v_fmac_f32_e32 v235, v18, v56
	v_fma_f32 v236, v34, v56, -v236
	v_cvt_pk_bf16_f32 v235, v235, v235
	v_cvt_pk_bf16_f32 v236, v236, v236
	ds_write_b16 v237, v235 offset:7424
	ds_write_b16 v237, v236 offset:7488
	v_mul_f32_e32 v235, v35, v228
	v_mul_f32_e32 v236, v19, v228
	v_fmac_f32_e32 v235, v19, v57
	v_fma_f32 v236, v35, v57, -v236
	v_cvt_pk_bf16_f32 v235, v235, v235
	v_cvt_pk_bf16_f32 v236, v236, v236
	ds_write_b16 v237, v235 offset:7552
	ds_write_b16 v237, v236 offset:7616
	v_or_b32_e32 v231, 0x4000, v229
	v_add_u32_e32 v232, 0x8000, v231
	global_load_dword v42, v231, s[4:5]
	global_load_dword v213, v232, s[4:5]
	v_or_b32_e32 v231, 0x4100, v229
	v_add_u32_e32 v232, 0x8000, v231
	global_load_dword v43, v231, s[4:5]
	global_load_dword v214, v232, s[4:5]
	v_or_b32_e32 v231, 0x4200, v229
	v_add_u32_e32 v232, 0x8000, v231
	global_load_dword v44, v231, s[4:5]
	global_load_dword v215, v232, s[4:5]
	v_or_b32_e32 v231, 0x4300, v229
	v_add_u32_e32 v232, 0x8000, v231
	global_load_dword v45, v231, s[4:5]
	global_load_dword v216, v232, s[4:5]
	v_or_b32_e32 v231, 0x4800, v229
	v_add_u32_e32 v232, 0x8000, v231
	global_load_dword v46, v231, s[4:5]
	global_load_dword v217, v232, s[4:5]
	v_or_b32_e32 v231, 0x4900, v229
	v_add_u32_e32 v232, 0x8000, v231
	global_load_dword v47, v231, s[4:5]
	global_load_dword v218, v232, s[4:5]
	v_or_b32_e32 v231, 0x4a00, v229
	v_add_u32_e32 v232, 0x8000, v231
	global_load_dword v48, v231, s[4:5]
	global_load_dword v219, v232, s[4:5]
	v_or_b32_e32 v231, 0x4b00, v229
	v_add_u32_e32 v232, 0x8000, v231
	global_load_dword v49, v231, s[4:5]
	global_load_dword v220, v232, s[4:5]
	v_or_b32_e32 v231, 0x5000, v229
	v_add_u32_e32 v232, 0x8000, v231
	global_load_dword v50, v231, s[4:5]
	global_load_dword v221, v232, s[4:5]
	v_or_b32_e32 v231, 0x5100, v229
	v_add_u32_e32 v232, 0x8000, v231
	global_load_dword v51, v231, s[4:5]
	global_load_dword v222, v232, s[4:5]
	v_or_b32_e32 v231, 0x5200, v229
	v_add_u32_e32 v232, 0x8000, v231
	global_load_dword v52, v231, s[4:5]
	global_load_dword v223, v232, s[4:5]
	v_or_b32_e32 v231, 0x5300, v229
	v_add_u32_e32 v232, 0x8000, v231
	global_load_dword v53, v231, s[4:5]
	global_load_dword v224, v232, s[4:5]
	v_or_b32_e32 v231, 0x5800, v229
	v_add_u32_e32 v232, 0x8000, v231
	global_load_dword v54, v231, s[4:5]
	global_load_dword v225, v232, s[4:5]
	v_or_b32_e32 v231, 0x5900, v229
	v_add_u32_e32 v232, 0x8000, v231
	global_load_dword v55, v231, s[4:5]
	global_load_dword v226, v232, s[4:5]
	v_or_b32_e32 v231, 0x5a00, v229
	v_add_u32_e32 v232, 0x8000, v231
	global_load_dword v56, v231, s[4:5]
	global_load_dword v227, v232, s[4:5]
	v_or_b32_e32 v231, 0x5b00, v229
	v_add_u32_e32 v232, 0x8000, v231
	global_load_dword v57, v231, s[4:5]
	global_load_dword v228, v232, s[4:5]
	s_waitcnt lgkmcnt(0)
	ds_read_b128 v[76:79], v239 offset:4096
	ds_read_b128 v[244:247], v239 offset:5120
	ds_read_b128 v[250:253], v239 offset:6144
	ds_read_b128 v[240:243], v239 offset:7168
	s_waitcnt lgkmcnt(3)
	v_add_u32_e32 v234, 0x200000, v233
	global_store_dwordx4 v234, v[76:79], s[6:7]
	s_waitcnt lgkmcnt(2)
	v_add_u32_e32 v234, 0x280000, v233
	global_store_dwordx4 v234, v[244:247], s[6:7]
	s_waitcnt lgkmcnt(1)
	v_add_u32_e32 v234, 0x300000, v233
	global_store_dwordx4 v234, v[250:253], s[6:7]
	s_waitcnt lgkmcnt(0)
	v_add_u32_e32 v234, 0x380000, v233
	global_store_dwordx4 v234, v[240:243], s[6:7]
	s_waitcnt vmcnt(32)
	v_mfma_f32_32x32x16_bf16 v[4:19], v[84:87], v[148:151], 0
	v_mfma_f32_32x32x16_bf16 v[4:19], v[88:91], v[152:155], v[4:19]
	v_xor_b32_e32 v68, 0x80008000, v88
	v_xor_b32_e32 v69, 0x80008000, v89
	v_xor_b32_e32 v70, 0x80008000, v90
	v_xor_b32_e32 v71, 0x80008000, v91
	v_mfma_f32_32x32x16_bf16 v[20:35], v[84:87], v[152:155], 0
	s_nop 0
	v_mfma_f32_32x32x16_bf16 v[20:35], v[68:71], v[148:151], v[20:35]
	v_mfma_f32_32x32x16_bf16 v[4:19], v[92:95], v[156:159], v[4:19]
	v_mfma_f32_32x32x16_bf16 v[4:19], v[96:99], v[160:163], v[4:19]
	v_xor_b32_e32 v68, 0x80008000, v96
	v_xor_b32_e32 v69, 0x80008000, v97
	v_xor_b32_e32 v70, 0x80008000, v98
	v_xor_b32_e32 v71, 0x80008000, v99
	v_mfma_f32_32x32x16_bf16 v[20:35], v[92:95], v[160:163], v[20:35]
	s_nop 0
	v_mfma_f32_32x32x16_bf16 v[20:35], v[68:71], v[156:159], v[20:35]
	v_mfma_f32_32x32x16_bf16 v[4:19], v[100:103], v[164:167], v[4:19]
	v_mfma_f32_32x32x16_bf16 v[4:19], v[104:107], v[168:171], v[4:19]
	v_xor_b32_e32 v68, 0x80008000, v104
	v_xor_b32_e32 v69, 0x80008000, v105
	v_xor_b32_e32 v70, 0x80008000, v106
	v_xor_b32_e32 v71, 0x80008000, v107
	v_mfma_f32_32x32x16_bf16 v[20:35], v[100:103], v[168:171], v[20:35]
	s_nop 0
	v_mfma_f32_32x32x16_bf16 v[20:35], v[68:71], v[164:167], v[20:35]
	v_mfma_f32_32x32x16_bf16 v[4:19], v[108:111], v[172:175], v[4:19]
	v_mfma_f32_32x32x16_bf16 v[4:19], v[112:115], v[176:179], v[4:19]
	v_xor_b32_e32 v68, 0x80008000, v112
	v_xor_b32_e32 v69, 0x80008000, v113
	v_xor_b32_e32 v70, 0x80008000, v114
	v_xor_b32_e32 v71, 0x80008000, v115
	v_mfma_f32_32x32x16_bf16 v[20:35], v[108:111], v[176:179], v[20:35]
	s_nop 0
	v_mfma_f32_32x32x16_bf16 v[20:35], v[68:71], v[172:175], v[20:35]
	v_mfma_f32_32x32x16_bf16 v[4:19], v[116:119], v[180:183], v[4:19]
	v_mfma_f32_32x32x16_bf16 v[4:19], v[120:123], v[184:187], v[4:19]
	v_xor_b32_e32 v68, 0x80008000, v120
	v_xor_b32_e32 v69, 0x80008000, v121
	v_xor_b32_e32 v70, 0x80008000, v122
	v_xor_b32_e32 v71, 0x80008000, v123
	v_mfma_f32_32x32x16_bf16 v[20:35], v[116:119], v[184:187], v[20:35]
	s_nop 0
; __device__ __forceinline__ bf16_t bf1(float v) { return (bf16_t)pk2(v, 0.f); }
; __device__ __forceinline__ void dft1_mfma(const bf16_t* U, bf16_t* YB, const bf16_t* A1, const float* TW, LAS unsigned char* tile, int gw, int NGW, int lane) {
;     ...
;             for (int kk = 0; kk < 8; ++kk) {
;                 const bf16x8 ac = *(const bf16x8*)(ap + 16 * kk), as = *(const bf16x8*)(ap + 128 + 16 * kk);
;                 const bf16x8 br = tr2(tile + offR + kk * 2048, 512), bi = tr2(tile + offI + kk * 2048, 512);
;                 aR = __builtin_amdgcn_mfma_f32_32x32x16_bf16(ac, br, aR, 0, 0, 0); aR = __builtin_amdgcn_mfma_f32_32x32x16_bf16(as, bi, aR, 0, 0, 0);
;                 aI = __builtin_amdgcn_mfma_f32_32x32x16_bf16(ac, bi, aI, 0, 0, 0); aI = __builtin_amdgcn_mfma_f32_32x32x16_bf16(negbf(as), br, aI, 0, 0, 0);
;             }
; #pragma unroll
;             for (int i = 0; i < 16; ++i) { const int ka = 32 * mb + 8 * (i >> 2) + 4 * hh + (i & 3); const float tc = TW[ka * 64 + sf], ts = TW[8192 + ka * 64 + sf];
;                 const float r2 = tc * aR[i] + ts * aI[i], i2 = tc * aI[i] - ts * aR[i]; bf16_t* op = YB + (size_t)(b * SEQ + ka * 64 + sf) * 512 + 128 * g + 32 * nh + r32;
;                 op[0] = bf1(r2); op[64] = bf1(i2); }
	v_mfma_f32_32x32x16_bf16 v[20:35], v[68:71], v[180:183], v[20:35]
	v_mfma_f32_32x32x16_bf16 v[4:19], v[124:127], v[188:191], v[4:19]
	v_mfma_f32_32x32x16_bf16 v[4:19], v[128:131], v[192:195], v[4:19]
	v_xor_b32_e32 v68, 0x80008000, v128
	v_xor_b32_e32 v69, 0x80008000, v129
	v_xor_b32_e32 v70, 0x80008000, v130
	v_xor_b32_e32 v71, 0x80008000, v131
	v_mfma_f32_32x32x16_bf16 v[20:35], v[124:127], v[192:195], v[20:35]
	s_nop 0
	v_mfma_f32_32x32x16_bf16 v[20:35], v[68:71], v[188:191], v[20:35]
	v_mfma_f32_32x32x16_bf16 v[4:19], v[132:135], v[196:199], v[4:19]
	v_mfma_f32_32x32x16_bf16 v[4:19], v[136:139], v[200:203], v[4:19]
	v_xor_b32_e32 v68, 0x80008000, v136
	v_xor_b32_e32 v69, 0x80008000, v137
	v_xor_b32_e32 v70, 0x80008000, v138
	v_xor_b32_e32 v71, 0x80008000, v139
	v_mfma_f32_32x32x16_bf16 v[20:35], v[132:135], v[200:203], v[20:35]
	s_nop 0
	v_mfma_f32_32x32x16_bf16 v[20:35], v[68:71], v[196:199], v[20:35]
	v_mfma_f32_32x32x16_bf16 v[4:19], v[140:143], v[204:207], v[4:19]
	v_mfma_f32_32x32x16_bf16 v[4:19], v[60:63], v[64:67], v[4:19]
	v_xor_b32_e32 v68, 0x80008000, v60
	v_xor_b32_e32 v69, 0x80008000, v61
	v_xor_b32_e32 v70, 0x80008000, v62
	v_xor_b32_e32 v71, 0x80008000, v63
	v_mfma_f32_32x32x16_bf16 v[20:35], v[140:143], v[64:67], v[20:35]
	s_nop 0
	v_mfma_f32_32x32x16_bf16 v[20:35], v[68:71], v[204:207], v[20:35]
	global_load_dwordx4 v[84:87], v[72:73], off
	global_load_dwordx4 v[88:91], v[72:73], off offset:256
	global_load_dwordx4 v[92:95], v[72:73], off offset:32
	global_load_dwordx4 v[96:99], v[72:73], off offset:288
	global_load_dwordx4 v[100:103], v[72:73], off offset:64
	global_load_dwordx4 v[104:107], v[72:73], off offset:320
	global_load_dwordx4 v[108:111], v[72:73], off offset:96
	global_load_dwordx4 v[112:115], v[72:73], off offset:352
	global_load_dwordx4 v[116:119], v[72:73], off offset:128
	global_load_dwordx4 v[120:123], v[72:73], off offset:384
	global_load_dwordx4 v[124:127], v[72:73], off offset:160
	global_load_dwordx4 v[128:131], v[72:73], off offset:416
	global_load_dwordx4 v[132:135], v[72:73], off offset:192
	global_load_dwordx4 v[136:139], v[72:73], off offset:448
	global_load_dwordx4 v[140:143], v[72:73], off offset:224
	global_load_dwordx4 v[60:63], v[72:73], off offset:480
	s_waitcnt vmcnt(16)
	s_nop 15
	v_mul_f32_e32 v235, v20, v213
	v_mul_f32_e32 v236, v4, v213
	v_fmac_f32_e32 v235, v4, v42
	v_fma_f32 v236, v20, v42, -v236
	v_cvt_pk_bf16_f32 v235, v235, v235
	v_cvt_pk_bf16_f32 v236, v236, v236
	ds_write_b16 v237, v235 offset:8192
	ds_write_b16 v237, v236 offset:8256
	v_mul_f32_e32 v235, v21, v214
	v_mul_f32_e32 v236, v5, v214
	v_fmac_f32_e32 v235, v5, v43
	v_fma_f32 v236, v21, v43, -v236
	v_cvt_pk_bf16_f32 v235, v235, v235
	v_cvt_pk_bf16_f32 v236, v236, v236
	ds_write_b16 v237, v235 offset:8320
	ds_write_b16 v237, v236 offset:8384
	v_mul_f32_e32 v235, v22, v215
	v_mul_f32_e32 v236, v6, v215
	v_fmac_f32_e32 v235, v6, v44
	v_fma_f32 v236, v22, v44, -v236
	v_cvt_pk_bf16_f32 v235, v235, v235
	v_cvt_pk_bf16_f32 v236, v236, v236
	ds_write_b16 v237, v235 offset:8448
	ds_write_b16 v237, v236 offset:8512
	v_mul_f32_e32 v235, v23, v216
	v_mul_f32_e32 v236, v7, v216
	v_fmac_f32_e32 v235, v7, v45
	v_fma_f32 v236, v23, v45, -v236
	v_cvt_pk_bf16_f32 v235, v235, v235
	v_cvt_pk_bf16_f32 v236, v236, v236
	ds_write_b16 v237, v235 offset:8576
	ds_write_b16 v237, v236 offset:8640
	v_mul_f32_e32 v235, v24, v217
	v_mul_f32_e32 v236, v8, v217
	v_fmac_f32_e32 v235, v8, v46
	v_fma_f32 v236, v24, v46, -v236
	v_cvt_pk_bf16_f32 v235, v235, v235
	v_cvt_pk_bf16_f32 v236, v236, v236
	ds_write_b16 v237, v235 offset:9216
	ds_write_b16 v237, v236 offset:9280
	v_mul_f32_e32 v235, v25, v218
	v_mul_f32_e32 v236, v9, v218
	v_fmac_f32_e32 v235, v9, v47
	v_fma_f32 v236, v25, v47, -v236
	v_cvt_pk_bf16_f32 v235, v235, v235
	v_cvt_pk_bf16_f32 v236, v236, v236
	ds_write_b16 v237, v235 offset:9344
	ds_write_b16 v237, v236 offset:9408
	v_mul_f32_e32 v235, v26, v219
	v_mul_f32_e32 v236, v10, v219
	v_fmac_f32_e32 v235, v10, v48
	v_fma_f32 v236, v26, v48, -v236
	v_cvt_pk_bf16_f32 v235, v235, v235
	v_cvt_pk_bf16_f32 v236, v236, v236
	ds_write_b16 v237, v235 offset:9472
	ds_write_b16 v237, v236 offset:9536
	v_mul_f32_e32 v235, v27, v220
	v_mul_f32_e32 v236, v11, v220
	v_fmac_f32_e32 v235, v11, v49
	v_fma_f32 v236, v27, v49, -v236
	v_cvt_pk_bf16_f32 v235, v235, v235
	v_cvt_pk_bf16_f32 v236, v236, v236
	ds_write_b16 v237, v235 offset:9600
	ds_write_b16 v237, v236 offset:9664
	v_mul_f32_e32 v235, v28, v221
	v_mul_f32_e32 v236, v12, v221
	v_fmac_f32_e32 v235, v12, v50
	v_fma_f32 v236, v28, v50, -v236
	v_cvt_pk_bf16_f32 v235, v235, v235
	v_cvt_pk_bf16_f32 v236, v236, v236
	ds_write_b16 v237, v235 offset:10240
	ds_write_b16 v237, v236 offset:10304
	v_mul_f32_e32 v235, v29, v222
	v_mul_f32_e32 v236, v13, v222
	v_fmac_f32_e32 v235, v13, v51
	v_fma_f32 v236, v29, v51, -v236
	v_cvt_pk_bf16_f32 v235, v235, v235
	v_cvt_pk_bf16_f32 v236, v236, v236
	ds_write_b16 v237, v235 offset:10368
	ds_write_b16 v237, v236 offset:10432
	v_mul_f32_e32 v235, v30, v223
	v_mul_f32_e32 v236, v14, v223
	v_fmac_f32_e32 v235, v14, v52
	v_fma_f32 v236, v30, v52, -v236
	v_cvt_pk_bf16_f32 v235, v235, v235
	v_cvt_pk_bf16_f32 v236, v236, v236
	ds_write_b16 v237, v235 offset:10496
	ds_write_b16 v237, v236 offset:10560
	v_mul_f32_e32 v235, v31, v224
	v_mul_f32_e32 v236, v15, v224
	v_fmac_f32_e32 v235, v15, v53
	v_fma_f32 v236, v31, v53, -v236
	v_cvt_pk_bf16_f32 v235, v235, v235
	v_cvt_pk_bf16_f32 v236, v236, v236
	ds_write_b16 v237, v235 offset:10624
	ds_write_b16 v237, v236 offset:10688
	v_mul_f32_e32 v235, v32, v225
	v_mul_f32_e32 v236, v16, v225
	v_fmac_f32_e32 v235, v16, v54
; __device__ __forceinline__ bf16_t bf1(float v) { return (bf16_t)pk2(v, 0.f); }
; __device__ __forceinline__ void dft1_mfma(const bf16_t* U, bf16_t* YB, const bf16_t* A1, const float* TW, LAS unsigned char* tile, int gw, int NGW, int lane) {
;     ...
;             for (int kk = 0; kk < 8; ++kk) {
;                 const bf16x8 ac = *(const bf16x8*)(ap + 16 * kk), as = *(const bf16x8*)(ap + 128 + 16 * kk);
;                 const bf16x8 br = tr2(tile + offR + kk * 2048, 512), bi = tr2(tile + offI + kk * 2048, 512);
;                 aR = __builtin_amdgcn_mfma_f32_32x32x16_bf16(ac, br, aR, 0, 0, 0); aR = __builtin_amdgcn_mfma_f32_32x32x16_bf16(as, bi, aR, 0, 0, 0);
;                 aI = __builtin_amdgcn_mfma_f32_32x32x16_bf16(ac, bi, aI, 0, 0, 0); aI = __builtin_amdgcn_mfma_f32_32x32x16_bf16(negbf(as), br, aI, 0, 0, 0);
;             }
; #pragma unroll
;             for (int i = 0; i < 16; ++i) { const int ka = 32 * mb + 8 * (i >> 2) + 4 * hh + (i & 3); const float tc = TW[ka * 64 + sf], ts = TW[8192 + ka * 64 + sf];
;                 const float r2 = tc * aR[i] + ts * aI[i], i2 = tc * aI[i] - ts * aR[i]; bf16_t* op = YB + (size_t)(b * SEQ + ka * 64 + sf) * 512 + 128 * g + 32 * nh + r32;
;                 op[0] = bf1(r2); op[64] = bf1(i2); }
	v_fma_f32 v236, v32, v54, -v236
	v_cvt_pk_bf16_f32 v235, v235, v235
	v_cvt_pk_bf16_f32 v236, v236, v236
	ds_write_b16 v237, v235 offset:11264
	ds_write_b16 v237, v236 offset:11328
	v_mul_f32_e32 v235, v33, v226
	v_mul_f32_e32 v236, v17, v226
	v_fmac_f32_e32 v235, v17, v55
	v_fma_f32 v236, v33, v55, -v236
	v_cvt_pk_bf16_f32 v235, v235, v235
	v_cvt_pk_bf16_f32 v236, v236, v236
	ds_write_b16 v237, v235 offset:11392
	ds_write_b16 v237, v236 offset:11456
	v_mul_f32_e32 v235, v34, v227
	v_mul_f32_e32 v236, v18, v227
	v_fmac_f32_e32 v235, v18, v56
	v_fma_f32 v236, v34, v56, -v236
	v_cvt_pk_bf16_f32 v235, v235, v235
	v_cvt_pk_bf16_f32 v236, v236, v236
	ds_write_b16 v237, v235 offset:11520
	ds_write_b16 v237, v236 offset:11584
	v_mul_f32_e32 v235, v35, v228
	v_mul_f32_e32 v236, v19, v228
	v_fmac_f32_e32 v235, v19, v57
	v_fma_f32 v236, v35, v57, -v236
	v_cvt_pk_bf16_f32 v235, v235, v235
	v_cvt_pk_bf16_f32 v236, v236, v236
	ds_write_b16 v237, v235 offset:11648
	ds_write_b16 v237, v236 offset:11712
	v_or_b32_e32 v231, 0x6000, v229
	v_add_u32_e32 v232, 0x8000, v231
	global_load_dword v42, v231, s[4:5]
	global_load_dword v213, v232, s[4:5]
	v_or_b32_e32 v231, 0x6100, v229
	v_add_u32_e32 v232, 0x8000, v231
	global_load_dword v43, v231, s[4:5]
	global_load_dword v214, v232, s[4:5]
	v_or_b32_e32 v231, 0x6200, v229
	v_add_u32_e32 v232, 0x8000, v231
	global_load_dword v44, v231, s[4:5]
	global_load_dword v215, v232, s[4:5]
	v_or_b32_e32 v231, 0x6300, v229
	v_add_u32_e32 v232, 0x8000, v231
	global_load_dword v45, v231, s[4:5]
	global_load_dword v216, v232, s[4:5]
	v_or_b32_e32 v231, 0x6800, v229
	v_add_u32_e32 v232, 0x8000, v231
	global_load_dword v46, v231, s[4:5]
	global_load_dword v217, v232, s[4:5]
	v_or_b32_e32 v231, 0x6900, v229
	v_add_u32_e32 v232, 0x8000, v231
	global_load_dword v47, v231, s[4:5]
	global_load_dword v218, v232, s[4:5]
	v_or_b32_e32 v231, 0x6a00, v229
	v_add_u32_e32 v232, 0x8000, v231
	global_load_dword v48, v231, s[4:5]
	global_load_dword v219, v232, s[4:5]
	v_or_b32_e32 v231, 0x6b00, v229
	v_add_u32_e32 v232, 0x8000, v231
	global_load_dword v49, v231, s[4:5]
	global_load_dword v220, v232, s[4:5]
	v_or_b32_e32 v231, 0x7000, v229
	v_add_u32_e32 v232, 0x8000, v231
	global_load_dword v50, v231, s[4:5]
	global_load_dword v221, v232, s[4:5]
	v_or_b32_e32 v231, 0x7100, v229
	v_add_u32_e32 v232, 0x8000, v231
	global_load_dword v51, v231, s[4:5]
	global_load_dword v222, v232, s[4:5]
	v_or_b32_e32 v231, 0x7200, v229
	v_add_u32_e32 v232, 0x8000, v231
	global_load_dword v52, v231, s[4:5]
	global_load_dword v223, v232, s[4:5]
	v_or_b32_e32 v231, 0x7300, v229
	v_add_u32_e32 v232, 0x8000, v231
	global_load_dword v53, v231, s[4:5]
	global_load_dword v224, v232, s[4:5]
	v_or_b32_e32 v231, 0x7800, v229
	v_add_u32_e32 v232, 0x8000, v231
	global_load_dword v54, v231, s[4:5]
	global_load_dword v225, v232, s[4:5]
	v_or_b32_e32 v231, 0x7900, v229
	v_add_u32_e32 v232, 0x8000, v231
	global_load_dword v55, v231, s[4:5]
	global_load_dword v226, v232, s[4:5]
	v_or_b32_e32 v231, 0x7a00, v229
	v_add_u32_e32 v232, 0x8000, v231
	global_load_dword v56, v231, s[4:5]
	global_load_dword v227, v232, s[4:5]
	v_or_b32_e32 v231, 0x7b00, v229
	v_add_u32_e32 v232, 0x8000, v231
	global_load_dword v57, v231, s[4:5]
	global_load_dword v228, v232, s[4:5]
	s_waitcnt lgkmcnt(0)
	ds_read_b128 v[76:79], v239 offset:8192
	ds_read_b128 v[244:247], v239 offset:9216
	ds_read_b128 v[250:253], v239 offset:10240
	ds_read_b128 v[240:243], v239 offset:11264
	s_waitcnt lgkmcnt(3)
	v_add_u32_e32 v234, 0x400000, v233
	global_store_dwordx4 v234, v[76:79], s[6:7]
	s_waitcnt lgkmcnt(2)
	v_add_u32_e32 v234, 0x480000, v233
	global_store_dwordx4 v234, v[244:247], s[6:7]
	s_waitcnt lgkmcnt(1)
	v_add_u32_e32 v234, 0x500000, v233
	global_store_dwordx4 v234, v[250:253], s[6:7]
	s_waitcnt lgkmcnt(0)
	v_add_u32_e32 v234, 0x580000, v233
	global_store_dwordx4 v234, v[240:243], s[6:7]
	s_waitcnt vmcnt(32)
	v_mfma_f32_32x32x16_bf16 v[4:19], v[84:87], v[148:151], 0
	v_mfma_f32_32x32x16_bf16 v[4:19], v[88:91], v[152:155], v[4:19]
	v_xor_b32_e32 v68, 0x80008000, v88
	v_xor_b32_e32 v69, 0x80008000, v89
	v_xor_b32_e32 v70, 0x80008000, v90
	v_xor_b32_e32 v71, 0x80008000, v91
	v_mfma_f32_32x32x16_bf16 v[20:35], v[84:87], v[152:155], 0
	s_nop 0
	v_mfma_f32_32x32x16_bf16 v[20:35], v[68:71], v[148:151], v[20:35]
	v_mfma_f32_32x32x16_bf16 v[4:19], v[92:95], v[156:159], v[4:19]
	v_mfma_f32_32x32x16_bf16 v[4:19], v[96:99], v[160:163], v[4:19]
	v_xor_b32_e32 v68, 0x80008000, v96
	v_xor_b32_e32 v69, 0x80008000, v97
	v_xor_b32_e32 v70, 0x80008000, v98
	v_xor_b32_e32 v71, 0x80008000, v99
	v_mfma_f32_32x32x16_bf16 v[20:35], v[92:95], v[160:163], v[20:35]
	s_nop 0
	v_mfma_f32_32x32x16_bf16 v[20:35], v[68:71], v[156:159], v[20:35]
	v_mfma_f32_32x32x16_bf16 v[4:19], v[100:103], v[164:167], v[4:19]
	v_mfma_f32_32x32x16_bf16 v[4:19], v[104:107], v[168:171], v[4:19]
	v_xor_b32_e32 v68, 0x80008000, v104
	v_xor_b32_e32 v69, 0x80008000, v105
	v_xor_b32_e32 v70, 0x80008000, v106
	v_xor_b32_e32 v71, 0x80008000, v107
	v_mfma_f32_32x32x16_bf16 v[20:35], v[100:103], v[168:171], v[20:35]
	s_nop 0
	v_mfma_f32_32x32x16_bf16 v[20:35], v[68:71], v[164:167], v[20:35]
	v_mfma_f32_32x32x16_bf16 v[4:19], v[108:111], v[172:175], v[4:19]
	v_mfma_f32_32x32x16_bf16 v[4:19], v[112:115], v[176:179], v[4:19]
	v_xor_b32_e32 v68, 0x80008000, v112
	v_xor_b32_e32 v69, 0x80008000, v113
	v_xor_b32_e32 v70, 0x80008000, v114
	v_xor_b32_e32 v71, 0x80008000, v115
	v_mfma_f32_32x32x16_bf16 v[20:35], v[108:111], v[176:179], v[20:35]
	s_nop 0
	v_mfma_f32_32x32x16_bf16 v[20:35], v[68:71], v[172:175], v[20:35]
	v_mfma_f32_32x32x16_bf16 v[4:19], v[116:119], v[180:183], v[4:19]
; __device__ __forceinline__ bf16_t bf1(float v) { return (bf16_t)pk2(v, 0.f); }
; #define LDS_WAIT() asm volatile("s_waitcnt lgkmcnt(0)" ::: "memory")
; __device__ __forceinline__ void dft1_mfma(const bf16_t* U, bf16_t* YB, const bf16_t* A1, const float* TW, LAS unsigned char* tile, int gw, int NGW, int lane) {
;     ...
;             for (int kk = 0; kk < 8; ++kk) {
;                 const bf16x8 ac = *(const bf16x8*)(ap + 16 * kk), as = *(const bf16x8*)(ap + 128 + 16 * kk);
;                 const bf16x8 br = tr2(tile + offR + kk * 2048, 512), bi = tr2(tile + offI + kk * 2048, 512);
;                 aR = __builtin_amdgcn_mfma_f32_32x32x16_bf16(ac, br, aR, 0, 0, 0); aR = __builtin_amdgcn_mfma_f32_32x32x16_bf16(as, bi, aR, 0, 0, 0);
;                 aI = __builtin_amdgcn_mfma_f32_32x32x16_bf16(ac, bi, aI, 0, 0, 0); aI = __builtin_amdgcn_mfma_f32_32x32x16_bf16(negbf(as), br, aI, 0, 0, 0);
;             }
; #pragma unroll
;             for (int i = 0; i < 16; ++i) { const int ka = 32 * mb + 8 * (i >> 2) + 4 * hh + (i & 3); const float tc = TW[ka * 64 + sf], ts = TW[8192 + ka * 64 + sf];
;                 const float r2 = tc * aR[i] + ts * aI[i], i2 = tc * aI[i] - ts * aR[i]; bf16_t* op = YB + (size_t)(b * SEQ + ka * 64 + sf) * 512 + 128 * g + 32 * nh + r32;
;                 op[0] = bf1(r2); op[64] = bf1(i2); }
;         }
;         LDS_WAIT();
	v_mfma_f32_32x32x16_bf16 v[4:19], v[120:123], v[184:187], v[4:19]
	v_xor_b32_e32 v68, 0x80008000, v120
	v_xor_b32_e32 v69, 0x80008000, v121
	v_xor_b32_e32 v70, 0x80008000, v122
	v_xor_b32_e32 v71, 0x80008000, v123
	v_mfma_f32_32x32x16_bf16 v[20:35], v[116:119], v[184:187], v[20:35]
	s_nop 0
	v_mfma_f32_32x32x16_bf16 v[20:35], v[68:71], v[180:183], v[20:35]
	v_mfma_f32_32x32x16_bf16 v[4:19], v[124:127], v[188:191], v[4:19]
	v_mfma_f32_32x32x16_bf16 v[4:19], v[128:131], v[192:195], v[4:19]
	v_xor_b32_e32 v68, 0x80008000, v128
	v_xor_b32_e32 v69, 0x80008000, v129
	v_xor_b32_e32 v70, 0x80008000, v130
	v_xor_b32_e32 v71, 0x80008000, v131
	v_mfma_f32_32x32x16_bf16 v[20:35], v[124:127], v[192:195], v[20:35]
	s_nop 0
	v_mfma_f32_32x32x16_bf16 v[20:35], v[68:71], v[188:191], v[20:35]
	v_mfma_f32_32x32x16_bf16 v[4:19], v[132:135], v[196:199], v[4:19]
	v_mfma_f32_32x32x16_bf16 v[4:19], v[136:139], v[200:203], v[4:19]
	v_xor_b32_e32 v68, 0x80008000, v136
	v_xor_b32_e32 v69, 0x80008000, v137
	v_xor_b32_e32 v70, 0x80008000, v138
	v_xor_b32_e32 v71, 0x80008000, v139
	v_mfma_f32_32x32x16_bf16 v[20:35], v[132:135], v[200:203], v[20:35]
	s_nop 0
	v_mfma_f32_32x32x16_bf16 v[20:35], v[68:71], v[196:199], v[20:35]
	v_mfma_f32_32x32x16_bf16 v[4:19], v[140:143], v[204:207], v[4:19]
	v_mfma_f32_32x32x16_bf16 v[4:19], v[60:63], v[64:67], v[4:19]
	v_xor_b32_e32 v68, 0x80008000, v60
	v_xor_b32_e32 v69, 0x80008000, v61
	v_xor_b32_e32 v70, 0x80008000, v62
	v_xor_b32_e32 v71, 0x80008000, v63
	v_mfma_f32_32x32x16_bf16 v[20:35], v[140:143], v[64:67], v[20:35]
	s_nop 0
	v_mfma_f32_32x32x16_bf16 v[20:35], v[68:71], v[204:207], v[20:35]
	s_waitcnt vmcnt(0)
	s_nop 15
	v_mul_f32_e32 v235, v20, v213
	v_mul_f32_e32 v236, v4, v213
	v_fmac_f32_e32 v235, v4, v42
	v_fma_f32 v236, v20, v42, -v236
	v_cvt_pk_bf16_f32 v235, v235, v235
	v_cvt_pk_bf16_f32 v236, v236, v236
	ds_write_b16 v237, v235 offset:12288
	ds_write_b16 v237, v236 offset:12352
	v_mul_f32_e32 v235, v21, v214
	v_mul_f32_e32 v236, v5, v214
	v_fmac_f32_e32 v235, v5, v43
	v_fma_f32 v236, v21, v43, -v236
	v_cvt_pk_bf16_f32 v235, v235, v235
	v_cvt_pk_bf16_f32 v236, v236, v236
	ds_write_b16 v237, v235 offset:12416
	ds_write_b16 v237, v236 offset:12480
	v_mul_f32_e32 v235, v22, v215
	v_mul_f32_e32 v236, v6, v215
	v_fmac_f32_e32 v235, v6, v44
	v_fma_f32 v236, v22, v44, -v236
	v_cvt_pk_bf16_f32 v235, v235, v235
	v_cvt_pk_bf16_f32 v236, v236, v236
	ds_write_b16 v237, v235 offset:12544
	ds_write_b16 v237, v236 offset:12608
	v_mul_f32_e32 v235, v23, v216
	v_mul_f32_e32 v236, v7, v216
	v_fmac_f32_e32 v235, v7, v45
	v_fma_f32 v236, v23, v45, -v236
	v_cvt_pk_bf16_f32 v235, v235, v235
	v_cvt_pk_bf16_f32 v236, v236, v236
	ds_write_b16 v237, v235 offset:12672
	ds_write_b16 v237, v236 offset:12736
	v_mul_f32_e32 v235, v24, v217
	v_mul_f32_e32 v236, v8, v217
	v_fmac_f32_e32 v235, v8, v46
	v_fma_f32 v236, v24, v46, -v236
	v_cvt_pk_bf16_f32 v235, v235, v235
	v_cvt_pk_bf16_f32 v236, v236, v236
	ds_write_b16 v237, v235 offset:13312
	ds_write_b16 v237, v236 offset:13376
	v_mul_f32_e32 v235, v25, v218
	v_mul_f32_e32 v236, v9, v218
	v_fmac_f32_e32 v235, v9, v47
	v_fma_f32 v236, v25, v47, -v236
	v_cvt_pk_bf16_f32 v235, v235, v235
	v_cvt_pk_bf16_f32 v236, v236, v236
	ds_write_b16 v237, v235 offset:13440
	ds_write_b16 v237, v236 offset:13504
	v_mul_f32_e32 v235, v26, v219
	v_mul_f32_e32 v236, v10, v219
	v_fmac_f32_e32 v235, v10, v48
	v_fma_f32 v236, v26, v48, -v236
	v_cvt_pk_bf16_f32 v235, v235, v235
	v_cvt_pk_bf16_f32 v236, v236, v236
	ds_write_b16 v237, v235 offset:13568
	ds_write_b16 v237, v236 offset:13632
	v_mul_f32_e32 v235, v27, v220
	v_mul_f32_e32 v236, v11, v220
	v_fmac_f32_e32 v235, v11, v49
	v_fma_f32 v236, v27, v49, -v236
	v_cvt_pk_bf16_f32 v235, v235, v235
	v_cvt_pk_bf16_f32 v236, v236, v236
	ds_write_b16 v237, v235 offset:13696
	ds_write_b16 v237, v236 offset:13760
	v_mul_f32_e32 v235, v28, v221
	v_mul_f32_e32 v236, v12, v221
	v_fmac_f32_e32 v235, v12, v50
	v_fma_f32 v236, v28, v50, -v236
	v_cvt_pk_bf16_f32 v235, v235, v235
	v_cvt_pk_bf16_f32 v236, v236, v236
	ds_write_b16 v237, v235 offset:14336
	ds_write_b16 v237, v236 offset:14400
	v_mul_f32_e32 v235, v29, v222
	v_mul_f32_e32 v236, v13, v222
	v_fmac_f32_e32 v235, v13, v51
	v_fma_f32 v236, v29, v51, -v236
	v_cvt_pk_bf16_f32 v235, v235, v235
	v_cvt_pk_bf16_f32 v236, v236, v236
	ds_write_b16 v237, v235 offset:14464
	ds_write_b16 v237, v236 offset:14528
	v_mul_f32_e32 v235, v30, v223
	v_mul_f32_e32 v236, v14, v223
	v_fmac_f32_e32 v235, v14, v52
	v_fma_f32 v236, v30, v52, -v236
	v_cvt_pk_bf16_f32 v235, v235, v235
	v_cvt_pk_bf16_f32 v236, v236, v236
	ds_write_b16 v237, v235 offset:14592
	ds_write_b16 v237, v236 offset:14656
	v_mul_f32_e32 v235, v31, v224
	v_mul_f32_e32 v236, v15, v224
	v_fmac_f32_e32 v235, v15, v53
	v_fma_f32 v236, v31, v53, -v236
	v_cvt_pk_bf16_f32 v235, v235, v235
	v_cvt_pk_bf16_f32 v236, v236, v236
	ds_write_b16 v237, v235 offset:14720
	ds_write_b16 v237, v236 offset:14784
	v_mul_f32_e32 v235, v32, v225
	v_mul_f32_e32 v236, v16, v225
	v_fmac_f32_e32 v235, v16, v54
	v_fma_f32 v236, v32, v54, -v236
	v_cvt_pk_bf16_f32 v235, v235, v235
	v_cvt_pk_bf16_f32 v236, v236, v236
	ds_write_b16 v237, v235 offset:15360
	ds_write_b16 v237, v236 offset:15424
	v_mul_f32_e32 v235, v33, v226
	v_mul_f32_e32 v236, v17, v226
	v_fmac_f32_e32 v235, v17, v55
	v_fma_f32 v236, v33, v55, -v236
	v_cvt_pk_bf16_f32 v235, v235, v235
	v_cvt_pk_bf16_f32 v236, v236, v236
	ds_write_b16 v237, v235 offset:15488
	ds_write_b16 v237, v236 offset:15552
	v_mul_f32_e32 v235, v34, v227
	v_mul_f32_e32 v236, v18, v227
	v_fmac_f32_e32 v235, v18, v56
	v_fma_f32 v236, v34, v56, -v236
	v_cvt_pk_bf16_f32 v235, v235, v235
	v_cvt_pk_bf16_f32 v236, v236, v236
	ds_write_b16 v237, v235 offset:15616
	ds_write_b16 v237, v236 offset:15680
	v_mul_f32_e32 v235, v35, v228
	v_mul_f32_e32 v236, v19, v228
	v_fmac_f32_e32 v235, v19, v57
	v_fma_f32 v236, v35, v57, -v236
	v_cvt_pk_bf16_f32 v235, v235, v235
	v_cvt_pk_bf16_f32 v236, v236, v236
	ds_write_b16 v237, v235 offset:15744
	ds_write_b16 v237, v236 offset:15808
	s_waitcnt lgkmcnt(0)
	ds_read_b128 v[76:79], v239 offset:12288
	ds_read_b128 v[244:247], v239 offset:13312
	ds_read_b128 v[250:253], v239 offset:14336
	ds_read_b128 v[240:243], v239 offset:15360
	s_waitcnt lgkmcnt(3)
	v_add_u32_e32 v234, 0x600000, v233
	global_store_dwordx4 v234, v[76:79], s[6:7]
	s_waitcnt lgkmcnt(2)
	v_add_u32_e32 v234, 0x680000, v233
	global_store_dwordx4 v234, v[244:247], s[6:7]
	s_waitcnt lgkmcnt(1)
	v_add_u32_e32 v234, 0x700000, v233
	global_store_dwordx4 v234, v[250:253], s[6:7]
	s_waitcnt lgkmcnt(0)
	v_add_u32_e32 v234, 0x780000, v233
	global_store_dwordx4 v234, v[240:243], s[6:7]
	s_waitcnt lgkmcnt(0)
	s_cbranch_scc0 .LBB0_697
	s_branch .LBB0_181
